# removed redundant setprio pairs and redundant post-barrier lgkmcnt waits in all GEMM K-loops
# speedup vs baseline: 1.0129x; 1.0044x over previous
; #define PG8_STAGE(bufoff, gbase, voff) do { _Pragma("unroll") for (int _i = 0; _i < 2; ++_i) \
;         __builtin_amdgcn_global_load_lds((const unsigned*)((const char*)(gbase) + (voff)[_i]), (PG8_LAS unsigned*)(lds + (bufoff) + ldsw + _i * 8192), 16, 0, 0); } while (0)
; #define PG8_LDA(dst, b, h) do { _Pragma("unroll") for (int m = 0; m < 4; ++m) _Pragma("unroll") for (int k = 0; k < 2; ++k) dst[m][k] = *(const PG8_LAS bf16x8*)(lds + PG8_SA(b, h) + aoff + m * 2048 + k * 1024); } while (0)
; #define PG8_LDB(dst, b, h) do { _Pragma("unroll") for (int n = 0; n < 2; ++n) _Pragma("unroll") for (int k = 0; k < 2; ++k) dst[n][k] = *(const PG8_LAS bf16x8*)(lds + PG8_SB(b, h) + boff + n * 2048 + k * 1024); } while (0)
; #define PG8_MMA(ai, bj, At, Bt) do { __builtin_amdgcn_s_setprio(1); _Pragma("unroll") for (int m = 0; m < 4; ++m) _Pragma("unroll") for (int n = 0; n < 2; ++n) _Pragma("unroll") for (int k = 0; k < 2; ++k) \
;         acc[ai][bj][m][n] = __builtin_amdgcn_mfma_f32_16x16x32_bf16(Bt[n][k], At[m][k], acc[ai][bj][m][n], 0, 0, 0); __builtin_amdgcn_s_setprio(0); } while (0)
; #define PG8_WAIT_V(n) asm volatile("s_waitcnt vmcnt(" #n ")" ::: "memory")
; #define PG8_WAIT_L(n) asm volatile("s_waitcnt lgkmcnt(" #n ")" ::: "memory")
; #define PG8_BAR __builtin_amdgcn_s_barrier()
; #define PG8_SCHED __builtin_amdgcn_sched_barrier(0)
; template <class Epi, class Sched, bool ALIGN_EPI = false, bool SP2 = false>
; __device__ __forceinline__ void gemm_phase(PG8_LAS unsigned char* lds, const Gemm g, const Sched& S, const Epi& E) {
;     ...
;             PG8_LDB(B0, 0, 0); PG8_LDB(B1, 0, 1); PG8_SCHED; PG8_LDA(At, 0, 0); PG8_STAGE(PG8_SA(1, 1), a1 + hstep, voffA);
;             PG8_WAIT_V(8); PG8_WAIT_L(0); PG8_BAR; PG8_MMA(0, 0, At, B0); PG8_MMA(0, 1, At, B1); PG8_BAR; PG8_SCHED;
;             PG8_LDA(At, 0, 1); PG8_STAGE(PG8_SB(0, 0), b2, voffB); PG8_STAGE(PG8_SB(0, 1), b2 + hstep, voffB); PG8_STAGE(PG8_SA(0, 0), a2, voffA);
;             PG8_WAIT_V(8); PG8_WAIT_L(0); PG8_BAR; PG8_MMA(1, 0, At, B0); PG8_MMA(1, 1, At, B1); PG8_BAR; PG8_SCHED;
.LBB0_123:
	s_add_u32 s8, s6, 0xfff80080
	s_addc_u32 s9, s7, -1
	s_add_i32 s43, 0, 0x10000
	s_cmp_eq_u32 s42, 28
	s_cselect_b32 s23, s15, s9
	s_cselect_b32 s22, s24, s8
	s_cselect_b32 s9, s17, s41
	s_cselect_b32 s8, s25, s40
	s_add_i32 s48, 0, 0x14000
	v_add_u32_e32 v172, s43, v165
	v_add_u32_e32 v188, s48, v165
	ds_read_b128 v[156:159], v172
	ds_read_b128 v[160:163], v172 offset:1024
	ds_read_b128 v[168:171], v172 offset:2048
	ds_read_b128 v[172:175], v172 offset:3072
	ds_read_b128 v[176:179], v188
	ds_read_b128 v[180:183], v188 offset:1024
	ds_read_b128 v[184:187], v188 offset:2048
	ds_read_b128 v[188:191], v188 offset:3072
	v_lshl_add_u64 v[228:229], s[6:7], 0, v[152:153]
	s_add_i32 m0, s31, 0xc000
	ds_read_b128 v[192:195], v167
	ds_read_b128 v[196:199], v167 offset:1024
	ds_read_b128 v[200:203], v167 offset:2048
	ds_read_b128 v[204:207], v167 offset:3072
	ds_read_b128 v[208:211], v167 offset:4096
	ds_read_b128 v[212:215], v167 offset:5120
	ds_read_b128 v[216:219], v167 offset:6144
	ds_read_b128 v[224:227], v167 offset:7168
	global_load_lds_dwordx4 v[228:229], off
	v_lshl_add_u64 v[228:229], s[6:7], 0, v[154:155]
	s_add_i32 m0, s31, 0xe000
	s_nop 0
	global_load_lds_dwordx4 v[228:229], off
	s_waitcnt vmcnt(8)
	s_waitcnt lgkmcnt(0)
	s_barrier
	s_setprio 1
	v_mfma_f32_16x16x32_bf16 v[144:147], v[156:159], v[192:195], v[144:147]
	v_mfma_f32_16x16x32_bf16 v[122:125], v[168:171], v[192:195], v[122:125]
	v_mfma_f32_16x16x32_bf16 v[110:113], v[156:159], v[200:203], v[110:113]
	v_mfma_f32_16x16x32_bf16 v[106:109], v[168:171], v[200:203], v[106:109]
	v_mfma_f32_16x16x32_bf16 v[94:97], v[156:159], v[208:211], v[94:97]
	v_mfma_f32_16x16x32_bf16 v[90:93], v[168:171], v[208:211], v[90:93]
	v_mfma_f32_16x16x32_bf16 v[78:81], v[156:159], v[216:219], v[78:81]
	v_mfma_f32_16x16x32_bf16 v[74:77], v[168:171], v[216:219], v[74:77]
	v_mfma_f32_16x16x32_bf16 v[144:147], v[160:163], v[196:199], v[144:147]
	v_mfma_f32_16x16x32_bf16 v[122:125], v[172:175], v[196:199], v[122:125]
	v_mfma_f32_16x16x32_bf16 v[110:113], v[160:163], v[204:207], v[110:113]
	v_mfma_f32_16x16x32_bf16 v[106:109], v[172:175], v[204:207], v[106:109]
	v_mfma_f32_16x16x32_bf16 v[94:97], v[160:163], v[212:215], v[94:97]
	v_mfma_f32_16x16x32_bf16 v[90:93], v[172:175], v[212:215], v[90:93]
	v_mfma_f32_16x16x32_bf16 v[78:81], v[160:163], v[224:227], v[78:81]
	v_mfma_f32_16x16x32_bf16 v[74:77], v[172:175], v[224:227], v[74:77]
	v_mfma_f32_16x16x32_bf16 v[118:121], v[176:179], v[192:195], v[118:121]
	v_mfma_f32_16x16x32_bf16 v[114:117], v[184:187], v[192:195], v[114:117]
	v_mfma_f32_16x16x32_bf16 v[102:105], v[176:179], v[200:203], v[102:105]
	v_mfma_f32_16x16x32_bf16 v[98:101], v[184:187], v[200:203], v[98:101]
	v_mfma_f32_16x16x32_bf16 v[86:89], v[176:179], v[208:211], v[86:89]
	v_mfma_f32_16x16x32_bf16 v[82:85], v[184:187], v[208:211], v[82:85]
	v_mfma_f32_16x16x32_bf16 v[70:73], v[176:179], v[216:219], v[70:73]
	v_mfma_f32_16x16x32_bf16 v[66:69], v[184:187], v[216:219], v[66:69]
	v_mfma_f32_16x16x32_bf16 v[118:121], v[180:183], v[196:199], v[118:121]
	v_mfma_f32_16x16x32_bf16 v[114:117], v[188:191], v[196:199], v[114:117]
	v_mfma_f32_16x16x32_bf16 v[102:105], v[180:183], v[204:207], v[102:105]
	v_mfma_f32_16x16x32_bf16 v[98:101], v[188:191], v[204:207], v[98:101]
	v_mfma_f32_16x16x32_bf16 v[86:89], v[180:183], v[212:215], v[86:89]
	v_mfma_f32_16x16x32_bf16 v[82:85], v[188:191], v[212:215], v[82:85]
	v_mfma_f32_16x16x32_bf16 v[70:73], v[180:183], v[224:227], v[70:73]
	v_mfma_f32_16x16x32_bf16 v[66:69], v[188:191], v[224:227], v[66:69]
	s_setprio 0
	s_barrier
	s_add_i32 s43, s43, s30
	v_lshl_add_u64 v[228:229], s[8:9], 0, v[0:1]
	s_mov_b32 m0, s43
	ds_read_b128 v[192:195], v167 offset:16384
	ds_read_b128 v[196:199], v167 offset:17408
	ds_read_b128 v[200:203], v167 offset:18432
	ds_read_b128 v[204:207], v167 offset:19456
	ds_read_b128 v[208:211], v167 offset:20480
	ds_read_b128 v[212:215], v167 offset:21504
	ds_read_b128 v[216:219], v167 offset:22528
	ds_read_b128 v[224:227], v167 offset:23552
	global_load_lds_dwordx4 v[228:229], off
	s_add_i32 m0, s43, 0x2000
	s_add_u32 s82, s8, 0x80000
	v_lshl_add_u64 v[230:231], s[8:9], 0, v[126:127]
	s_addc_u32 s83, s9, 0
	s_add_i32 s43, s48, s30
	global_load_lds_dwordx4 v[230:231], off
	v_lshl_add_u64 v[232:233], s[82:83], 0, v[0:1]
	s_mov_b32 m0, s43
	v_lshl_add_u64 v[244:245], s[22:23], 0, v[148:149]
	global_load_lds_dwordx4 v[232:233], off
	v_lshl_add_u64 v[232:233], s[82:83], 0, v[126:127]
	s_add_i32 m0, s43, 0x2000
	s_nop 0
	global_load_lds_dwordx4 v[232:233], off
	v_lshl_add_u64 v[232:233], s[22:23], 0, v[150:151]
	s_mov_b32 m0, s31
	s_nop 0
	global_load_lds_dwordx4 v[232:233], off
	s_mov_b32 m0, s34
	s_nop 0
	global_load_lds_dwordx4 v[244:245], off
	s_waitcnt vmcnt(8)
	s_waitcnt lgkmcnt(0)
	s_barrier
; #define PG8_STAGE(bufoff, gbase, voff) do { _Pragma("unroll") for (int _i = 0; _i < 2; ++_i) \
;         __builtin_amdgcn_global_load_lds((const unsigned*)((const char*)(gbase) + (voff)[_i]), (PG8_LAS unsigned*)(lds + (bufoff) + ldsw + _i * 8192), 16, 0, 0); } while (0)
; #define PG8_LDA(dst, b, h) do { _Pragma("unroll") for (int m = 0; m < 4; ++m) _Pragma("unroll") for (int k = 0; k < 2; ++k) dst[m][k] = *(const PG8_LAS bf16x8*)(lds + PG8_SA(b, h) + aoff + m * 2048 + k * 1024); } while (0)
; #define PG8_LDB(dst, b, h) do { _Pragma("unroll") for (int n = 0; n < 2; ++n) _Pragma("unroll") for (int k = 0; k < 2; ++k) dst[n][k] = *(const PG8_LAS bf16x8*)(lds + PG8_SB(b, h) + boff + n * 2048 + k * 1024); } while (0)
; #define PG8_MMA(ai, bj, At, Bt) do { __builtin_amdgcn_s_setprio(1); _Pragma("unroll") for (int m = 0; m < 4; ++m) _Pragma("unroll") for (int n = 0; n < 2; ++n) _Pragma("unroll") for (int k = 0; k < 2; ++k) \
;         acc[ai][bj][m][n] = __builtin_amdgcn_mfma_f32_16x16x32_bf16(Bt[n][k], At[m][k], acc[ai][bj][m][n], 0, 0, 0); __builtin_amdgcn_s_setprio(0); } while (0)
; #define PG8_WAIT_V(n) asm volatile("s_waitcnt vmcnt(" #n ")" ::: "memory")
; #define PG8_WAIT_L(n) asm volatile("s_waitcnt lgkmcnt(" #n ")" ::: "memory")
; #define PG8_BAR __builtin_amdgcn_s_barrier()
; #define PG8_SCHED __builtin_amdgcn_sched_barrier(0)
; template <class Epi, class Sched, bool ALIGN_EPI = false, bool SP2 = false>
; __device__ __forceinline__ void gemm_phase(PG8_LAS unsigned char* lds, const Gemm g, const Sched& S, const Epi& E) {
;     ...
;             PG8_WAIT_V(8); PG8_WAIT_L(0); PG8_BAR; PG8_MMA(0, 0, At, B0); PG8_MMA(0, 1, At, B1); PG8_BAR; PG8_SCHED;
;             PG8_LDA(At, 0, 1); PG8_STAGE(PG8_SB(0, 0), b2, voffB); PG8_STAGE(PG8_SB(0, 1), b2 + hstep, voffB); PG8_STAGE(PG8_SA(0, 0), a2, voffA);
;             PG8_WAIT_V(8); PG8_WAIT_L(0); PG8_BAR; PG8_MMA(1, 0, At, B0); PG8_MMA(1, 1, At, B1); PG8_BAR; PG8_SCHED;
;             PG8_LDB(B0, 1, 0); PG8_LDB(B1, 1, 1); PG8_SCHED; PG8_LDA(At, 1, 0); PG8_STAGE(PG8_SA(0, 1), a2 + hstep, voffA);
;             PG8_WAIT_V(8); PG8_WAIT_L(0); PG8_BAR; PG8_MMA(0, 0, At, B0); PG8_MMA(0, 1, At, B1); PG8_BAR; PG8_SCHED;
	s_setprio 1
	v_mfma_f32_16x16x32_bf16 v[62:65], v[156:159], v[192:195], v[62:65]
	v_mfma_f32_16x16x32_bf16 v[58:61], v[168:171], v[192:195], v[58:61]
	v_mfma_f32_16x16x32_bf16 v[46:49], v[156:159], v[200:203], v[46:49]
	v_mfma_f32_16x16x32_bf16 v[42:45], v[168:171], v[200:203], v[42:45]
	v_mfma_f32_16x16x32_bf16 v[30:33], v[156:159], v[208:211], v[30:33]
	v_mfma_f32_16x16x32_bf16 v[26:29], v[168:171], v[208:211], v[26:29]
	v_mfma_f32_16x16x32_bf16 v[14:17], v[156:159], v[216:219], v[14:17]
	v_mfma_f32_16x16x32_bf16 v[10:13], v[168:171], v[216:219], v[10:13]
	v_mfma_f32_16x16x32_bf16 v[62:65], v[160:163], v[196:199], v[62:65]
	v_mfma_f32_16x16x32_bf16 v[58:61], v[172:175], v[196:199], v[58:61]
	v_mfma_f32_16x16x32_bf16 v[46:49], v[160:163], v[204:207], v[46:49]
	v_mfma_f32_16x16x32_bf16 v[42:45], v[172:175], v[204:207], v[42:45]
	v_mfma_f32_16x16x32_bf16 v[30:33], v[160:163], v[212:215], v[30:33]
	v_mfma_f32_16x16x32_bf16 v[26:29], v[172:175], v[212:215], v[26:29]
	v_mfma_f32_16x16x32_bf16 v[14:17], v[160:163], v[224:227], v[14:17]
	v_mfma_f32_16x16x32_bf16 v[10:13], v[172:175], v[224:227], v[10:13]
	v_mfma_f32_16x16x32_bf16 v[54:57], v[176:179], v[192:195], v[54:57]
	v_mfma_f32_16x16x32_bf16 v[50:53], v[184:187], v[192:195], v[50:53]
	v_mfma_f32_16x16x32_bf16 v[38:41], v[176:179], v[200:203], v[38:41]
	v_mfma_f32_16x16x32_bf16 v[34:37], v[184:187], v[200:203], v[34:37]
	v_mfma_f32_16x16x32_bf16 v[22:25], v[176:179], v[208:211], v[22:25]
	v_mfma_f32_16x16x32_bf16 v[18:21], v[184:187], v[208:211], v[18:21]
	v_mfma_f32_16x16x32_bf16 v[6:9], v[176:179], v[216:219], v[6:9]
	v_mfma_f32_16x16x32_bf16 v[2:5], v[184:187], v[216:219], v[2:5]
	v_mfma_f32_16x16x32_bf16 v[54:57], v[180:183], v[196:199], v[54:57]
	v_mfma_f32_16x16x32_bf16 v[50:53], v[188:191], v[196:199], v[50:53]
	v_mfma_f32_16x16x32_bf16 v[38:41], v[180:183], v[204:207], v[38:41]
	v_mfma_f32_16x16x32_bf16 v[34:37], v[188:191], v[204:207], v[34:37]
	v_mfma_f32_16x16x32_bf16 v[22:25], v[180:183], v[212:215], v[22:25]
	v_mfma_f32_16x16x32_bf16 v[18:21], v[188:191], v[212:215], v[18:21]
	v_mfma_f32_16x16x32_bf16 v[6:9], v[180:183], v[224:227], v[6:9]
	v_mfma_f32_16x16x32_bf16 v[2:5], v[188:191], v[224:227], v[2:5]
	s_setprio 0
	s_barrier
	s_add_i32 s43, 0, 0x18000
	s_add_i32 s48, 0, 0x1c000
	v_add_u32_e32 v172, s43, v165
	v_add_u32_e32 v188, s48, v165
	ds_read_b128 v[156:159], v172
	ds_read_b128 v[160:163], v172 offset:1024
	ds_read_b128 v[168:171], v172 offset:2048
	ds_read_b128 v[172:175], v172 offset:3072
	ds_read_b128 v[176:179], v188
	ds_read_b128 v[180:183], v188 offset:1024
	ds_read_b128 v[184:187], v188 offset:2048
	ds_read_b128 v[188:191], v188 offset:3072
	s_add_u32 s22, s22, 0x80000
	s_addc_u32 s23, s23, 0
	s_mov_b32 m0, s35
	v_lshl_add_u64 v[246:247], s[22:23], 0, v[150:151]
	ds_read_b128 v[192:195], v167 offset:32768
	ds_read_b128 v[196:199], v167 offset:33792
	ds_read_b128 v[200:203], v167 offset:34816
	ds_read_b128 v[204:207], v167 offset:35840
	ds_read_b128 v[208:211], v167 offset:36864
	ds_read_b128 v[212:215], v167 offset:37888
	ds_read_b128 v[216:219], v167 offset:38912
	ds_read_b128 v[224:227], v167 offset:39936
	global_load_lds_dwordx4 v[246:247], off
	v_lshl_add_u64 v[246:247], s[22:23], 0, v[148:149]
	s_mov_b32 m0, s36
	s_nop 0
	global_load_lds_dwordx4 v[246:247], off
	s_waitcnt vmcnt(8)
	s_waitcnt lgkmcnt(0)
	s_barrier
	s_setprio 1
	v_mfma_f32_16x16x32_bf16 v[144:147], v[156:159], v[192:195], v[144:147]
	v_mfma_f32_16x16x32_bf16 v[122:125], v[168:171], v[192:195], v[122:125]
	v_mfma_f32_16x16x32_bf16 v[110:113], v[156:159], v[200:203], v[110:113]
	v_mfma_f32_16x16x32_bf16 v[106:109], v[168:171], v[200:203], v[106:109]
	v_mfma_f32_16x16x32_bf16 v[94:97], v[156:159], v[208:211], v[94:97]
	v_mfma_f32_16x16x32_bf16 v[90:93], v[168:171], v[208:211], v[90:93]
	v_mfma_f32_16x16x32_bf16 v[78:81], v[156:159], v[216:219], v[78:81]
	v_mfma_f32_16x16x32_bf16 v[74:77], v[168:171], v[216:219], v[74:77]
	v_mfma_f32_16x16x32_bf16 v[144:147], v[160:163], v[196:199], v[144:147]
	v_mfma_f32_16x16x32_bf16 v[122:125], v[172:175], v[196:199], v[122:125]
	v_mfma_f32_16x16x32_bf16 v[110:113], v[160:163], v[204:207], v[110:113]
	v_mfma_f32_16x16x32_bf16 v[106:109], v[172:175], v[204:207], v[106:109]
	v_mfma_f32_16x16x32_bf16 v[94:97], v[160:163], v[212:215], v[94:97]
	v_mfma_f32_16x16x32_bf16 v[90:93], v[172:175], v[212:215], v[90:93]
	v_mfma_f32_16x16x32_bf16 v[78:81], v[160:163], v[224:227], v[78:81]
	v_mfma_f32_16x16x32_bf16 v[74:77], v[172:175], v[224:227], v[74:77]
	v_mfma_f32_16x16x32_bf16 v[118:121], v[176:179], v[192:195], v[118:121]
	v_mfma_f32_16x16x32_bf16 v[114:117], v[184:187], v[192:195], v[114:117]
	v_mfma_f32_16x16x32_bf16 v[102:105], v[176:179], v[200:203], v[102:105]
	v_mfma_f32_16x16x32_bf16 v[98:101], v[184:187], v[200:203], v[98:101]
	v_mfma_f32_16x16x32_bf16 v[86:89], v[176:179], v[208:211], v[86:89]
	v_mfma_f32_16x16x32_bf16 v[82:85], v[184:187], v[208:211], v[82:85]
	v_mfma_f32_16x16x32_bf16 v[70:73], v[176:179], v[216:219], v[70:73]
	v_mfma_f32_16x16x32_bf16 v[66:69], v[184:187], v[216:219], v[66:69]
	v_mfma_f32_16x16x32_bf16 v[118:121], v[180:183], v[196:199], v[118:121]
	v_mfma_f32_16x16x32_bf16 v[114:117], v[188:191], v[196:199], v[114:117]
	v_mfma_f32_16x16x32_bf16 v[102:105], v[180:183], v[204:207], v[102:105]
	v_mfma_f32_16x16x32_bf16 v[98:101], v[188:191], v[204:207], v[98:101]
	v_mfma_f32_16x16x32_bf16 v[86:89], v[180:183], v[212:215], v[86:89]
	v_mfma_f32_16x16x32_bf16 v[82:85], v[188:191], v[212:215], v[82:85]
	v_mfma_f32_16x16x32_bf16 v[70:73], v[180:183], v[224:227], v[70:73]
	v_mfma_f32_16x16x32_bf16 v[66:69], v[188:191], v[224:227], v[66:69]
	s_setprio 0
	s_barrier
; #define PG8_STAGE(bufoff, gbase, voff) do { _Pragma("unroll") for (int _i = 0; _i < 2; ++_i) \
;         __builtin_amdgcn_global_load_lds((const unsigned*)((const char*)(gbase) + (voff)[_i]), (PG8_LAS unsigned*)(lds + (bufoff) + ldsw + _i * 8192), 16, 0, 0); } while (0)
; #define PG8_LDA(dst, b, h) do { _Pragma("unroll") for (int m = 0; m < 4; ++m) _Pragma("unroll") for (int k = 0; k < 2; ++k) dst[m][k] = *(const PG8_LAS bf16x8*)(lds + PG8_SA(b, h) + aoff + m * 2048 + k * 1024); } while (0)
; #define PG8_MMA(ai, bj, At, Bt) do { __builtin_amdgcn_s_setprio(1); _Pragma("unroll") for (int m = 0; m < 4; ++m) _Pragma("unroll") for (int n = 0; n < 2; ++n) _Pragma("unroll") for (int k = 0; k < 2; ++k) \
;         acc[ai][bj][m][n] = __builtin_amdgcn_mfma_f32_16x16x32_bf16(Bt[n][k], At[m][k], acc[ai][bj][m][n], 0, 0, 0); __builtin_amdgcn_s_setprio(0); } while (0)
; #define PG8_WAIT_V(n) asm volatile("s_waitcnt vmcnt(" #n ")" ::: "memory")
; #define PG8_WAIT_L(n) asm volatile("s_waitcnt lgkmcnt(" #n ")" ::: "memory")
; #define PG8_BAR __builtin_amdgcn_s_barrier()
; #define PG8_SCHED __builtin_amdgcn_sched_barrier(0)
; template <class Epi, class Sched, bool ALIGN_EPI = false, bool SP2 = false>
; __device__ __forceinline__ void gemm_phase(PG8_LAS unsigned char* lds, const Gemm g, const Sched& S, const Epi& E) {
;     ...
;         for (int t = 0; t < nt; t += 2) {
;     ...
;             PG8_LDA(At, 1, 1); PG8_STAGE(PG8_SB(1, 0), b3, voffB); PG8_STAGE(PG8_SB(1, 1), b3 + hstep, voffB); PG8_STAGE(PG8_SA(1, 0), a3, voffA);
;             PG8_WAIT_V(8); PG8_WAIT_L(0); PG8_BAR; PG8_MMA(1, 0, At, B0); PG8_MMA(1, 1, At, B1); PG8_BAR; PG8_SCHED;
	s_add_i32 s22, s43, s30
	v_lshl_add_u64 v[228:229], v[228:229], 0, s[64:65]
	s_mov_b32 m0, s22
	ds_read_b128 v[192:195], v167 offset:49152
	ds_read_b128 v[196:199], v167 offset:50176
	ds_read_b128 v[200:203], v167 offset:51200
	ds_read_b128 v[204:207], v167 offset:52224
	ds_read_b128 v[208:211], v167 offset:53248
	ds_read_b128 v[212:215], v167 offset:54272
	ds_read_b128 v[216:219], v167 offset:55296
	ds_read_b128 v[224:227], v167 offset:56320
	global_load_lds_dwordx4 v[228:229], off
	s_add_i32 m0, s22, 0x2000
	s_add_u32 s8, s8, 0x80080
	v_lshl_add_u64 v[228:229], v[230:231], 0, s[64:65]
	s_addc_u32 s9, s9, 0
	s_add_i32 s22, s48, s30
	global_load_lds_dwordx4 v[228:229], off
	v_lshl_add_u64 v[228:229], s[8:9], 0, v[0:1]
	s_mov_b32 m0, s22
	s_nop 0
	global_load_lds_dwordx4 v[228:229], off
	v_lshl_add_u64 v[228:229], s[8:9], 0, v[126:127]
	s_add_i32 m0, s22, 0x2000
	s_nop 0
	global_load_lds_dwordx4 v[228:229], off
	v_lshl_add_u64 v[228:229], v[232:233], 0, s[64:65]
	s_mov_b32 m0, s37
	s_nop 0
	global_load_lds_dwordx4 v[228:229], off
	v_lshl_add_u64 v[228:229], v[244:245], 0, s[64:65]
	s_mov_b32 m0, s76
	s_nop 0
	global_load_lds_dwordx4 v[228:229], off
	s_waitcnt vmcnt(8)
	s_waitcnt lgkmcnt(0)
	s_barrier
	s_setprio 1
	v_mfma_f32_16x16x32_bf16 v[62:65], v[156:159], v[192:195], v[62:65]
	v_mfma_f32_16x16x32_bf16 v[58:61], v[168:171], v[192:195], v[58:61]
	v_mfma_f32_16x16x32_bf16 v[46:49], v[156:159], v[200:203], v[46:49]
	v_mfma_f32_16x16x32_bf16 v[42:45], v[168:171], v[200:203], v[42:45]
	v_mfma_f32_16x16x32_bf16 v[30:33], v[156:159], v[208:211], v[30:33]
	v_mfma_f32_16x16x32_bf16 v[26:29], v[168:171], v[208:211], v[26:29]
	v_mfma_f32_16x16x32_bf16 v[14:17], v[156:159], v[216:219], v[14:17]
	v_mfma_f32_16x16x32_bf16 v[10:13], v[168:171], v[216:219], v[10:13]
	v_mfma_f32_16x16x32_bf16 v[62:65], v[160:163], v[196:199], v[62:65]
	v_mfma_f32_16x16x32_bf16 v[58:61], v[172:175], v[196:199], v[58:61]
	v_mfma_f32_16x16x32_bf16 v[46:49], v[160:163], v[204:207], v[46:49]
	v_mfma_f32_16x16x32_bf16 v[42:45], v[172:175], v[204:207], v[42:45]
	v_mfma_f32_16x16x32_bf16 v[30:33], v[160:163], v[212:215], v[30:33]
	v_mfma_f32_16x16x32_bf16 v[26:29], v[172:175], v[212:215], v[26:29]
	v_mfma_f32_16x16x32_bf16 v[14:17], v[160:163], v[224:227], v[14:17]
	v_mfma_f32_16x16x32_bf16 v[10:13], v[172:175], v[224:227], v[10:13]
	v_mfma_f32_16x16x32_bf16 v[54:57], v[176:179], v[192:195], v[54:57]
	v_mfma_f32_16x16x32_bf16 v[50:53], v[184:187], v[192:195], v[50:53]
	v_mfma_f32_16x16x32_bf16 v[38:41], v[176:179], v[200:203], v[38:41]
	v_mfma_f32_16x16x32_bf16 v[34:37], v[184:187], v[200:203], v[34:37]
	v_mfma_f32_16x16x32_bf16 v[22:25], v[176:179], v[208:211], v[22:25]
	v_mfma_f32_16x16x32_bf16 v[18:21], v[184:187], v[208:211], v[18:21]
	v_mfma_f32_16x16x32_bf16 v[6:9], v[176:179], v[216:219], v[6:9]
	v_mfma_f32_16x16x32_bf16 v[2:5], v[184:187], v[216:219], v[2:5]
	v_mfma_f32_16x16x32_bf16 v[54:57], v[180:183], v[196:199], v[54:57]
	v_mfma_f32_16x16x32_bf16 v[50:53], v[188:191], v[196:199], v[50:53]
	v_mfma_f32_16x16x32_bf16 v[38:41], v[180:183], v[204:207], v[38:41]
	v_mfma_f32_16x16x32_bf16 v[34:37], v[188:191], v[204:207], v[34:37]
	v_mfma_f32_16x16x32_bf16 v[22:25], v[180:183], v[212:215], v[22:25]
	v_mfma_f32_16x16x32_bf16 v[18:21], v[188:191], v[212:215], v[18:21]
	v_mfma_f32_16x16x32_bf16 v[6:9], v[180:183], v[224:227], v[6:9]
	v_mfma_f32_16x16x32_bf16 v[2:5], v[188:191], v[224:227], v[2:5]
	s_setprio 0
	s_barrier
	s_add_i32 s42, s42, 2
	s_add_u32 s6, s6, 0x100
	s_addc_u32 s7, s7, 0
	s_add_u32 s40, s40, 0x100
	s_addc_u32 s41, s41, 0
	s_cmp_gt_u32 s42, 29
	s_cbranch_scc0 .LBB0_123
	s_and_b64 vcc, exec, s[12:13]
	s_cbranch_vccz .LBB0_126
	s_barrier

; #define PG8_STAGE(bufoff, gbase, voff) do { _Pragma("unroll") for (int _i = 0; _i < 2; ++_i) \
;         __builtin_amdgcn_global_load_lds((const unsigned*)((const char*)(gbase) + (voff)[_i]), (PG8_LAS unsigned*)(lds + (bufoff) + ldsw + _i * 8192), 16, 0, 0); } while (0)
; #define PG8_LDA(dst, b, h) do { _Pragma("unroll") for (int m = 0; m < 4; ++m) _Pragma("unroll") for (int k = 0; k < 2; ++k) dst[m][k] = *(const PG8_LAS bf16x8*)(lds + PG8_SA(b, h) + aoff + m * 2048 + k * 1024); } while (0)
; #define PG8_LDB(dst, b, h) do { _Pragma("unroll") for (int n = 0; n < 2; ++n) _Pragma("unroll") for (int k = 0; k < 2; ++k) dst[n][k] = *(const PG8_LAS bf16x8*)(lds + PG8_SB(b, h) + boff + n * 2048 + k * 1024); } while (0)
; #define PG8_MMA(ai, bj, At, Bt) do { __builtin_amdgcn_s_setprio(1); _Pragma("unroll") for (int m = 0; m < 4; ++m) _Pragma("unroll") for (int n = 0; n < 2; ++n) _Pragma("unroll") for (int k = 0; k < 2; ++k) \
;         acc[ai][bj][m][n] = __builtin_amdgcn_mfma_f32_16x16x32_bf16(Bt[n][k], At[m][k], acc[ai][bj][m][n], 0, 0, 0); __builtin_amdgcn_s_setprio(0); } while (0)
; #define PG8_WAIT_V(n) asm volatile("s_waitcnt vmcnt(" #n ")" ::: "memory")
; #define PG8_WAIT_L(n) asm volatile("s_waitcnt lgkmcnt(" #n ")" ::: "memory")
; template <class Epi, class Sched, bool ALIGN_EPI = false, bool SP2 = false>
; __device__ __forceinline__ void gemm_phase(PG8_LAS unsigned char* lds, const Gemm g, const Sched& S, const Epi& E) {
;     ...
;             const bool last = (t == nt - 2);
;             const char* a1 = cA + (size_t)(t + 1) * kstep;
;             const char* a2 = last ? nA : cA + (size_t)(t + 2) * kstep; const char* b2 = last ? nB : cB + (size_t)(t + 2) * kstep;
;             const char* a3 = a2 + kstep; const char* b3 = b2 + kstep;
;             if (last && has_next) S.a_ready(nxt);
;             if constexpr (SP2) {
;             PG8_LDB(B0, 0, 0); PG8_LDB(B1, 0, 1); PG8_SCHED; PG8_LDA(At, 0, 0); PG8_STAGE(PG8_SA(1, 1), a1 + hstep, voffA);
;             PG8_WAIT_V(8); PG8_WAIT_L(0); PG8_BAR; PG8_MMA(0, 0, At, B0); PG8_MMA(0, 1, At, B1); PG8_BAR; PG8_SCHED;
;             PG8_LDA(At, 0, 1); PG8_STAGE(PG8_SB(0, 0), b2, voffB); PG8_STAGE(PG8_SB(0, 1), b2 + hstep, voffB); PG8_STAGE(PG8_SA(0, 0), a2, voffA);
;             PG8_WAIT_V(8); PG8_WAIT_L(0); PG8_BAR; PG8_MMA(1, 0, At, B0); PG8_MMA(1, 1, At, B1); PG8_BAR; PG8_SCHED;
.LBB0_307:
	s_add_u32 s4, s42, s0
	s_addc_u32 s5, s43, s1
	s_add_u32 s4, s4, 0x2cc00100
	s_addc_u32 s5, s5, 0
	s_add_u32 s20, s48, s0
	s_addc_u32 s21, s67, s1
	s_add_i32 s22, 0, 0x10000
	s_cmpk_eq_i32 s0, 0xf00
	s_cselect_b32 s7, s55, s5
	s_cselect_b32 s6, s54, s4
	s_cselect_b32 s5, s53, s21
	s_cselect_b32 s4, s52, s20
	s_add_i32 s23, 0, 0x14000
	v_add_u32_e32 v172, s22, v158
	v_add_u32_e32 v188, s23, v158
	ds_read_b128 v[160:163], v172
	ds_read_b128 v[164:167], v172 offset:1024
	ds_read_b128 v[168:171], v172 offset:2048
	ds_read_b128 v[172:175], v172 offset:3072
	ds_read_b128 v[176:179], v188
	ds_read_b128 v[180:183], v188 offset:1024
	ds_read_b128 v[184:187], v188 offset:2048
	ds_read_b128 v[188:191], v188 offset:3072
	v_lshl_add_u64 v[228:229], v[152:153], 0, s[0:1]
	s_add_i32 m0, s12, 0xc000
	ds_read_b128 v[192:195], v159
	ds_read_b128 v[196:199], v159 offset:1024
	ds_read_b128 v[200:203], v159 offset:2048
	ds_read_b128 v[204:207], v159 offset:3072
	ds_read_b128 v[208:211], v159 offset:4096
	ds_read_b128 v[212:215], v159 offset:5120
	ds_read_b128 v[216:219], v159 offset:6144
	ds_read_b128 v[224:227], v159 offset:7168
	global_load_lds_dwordx4 v[228:229], off
	v_lshl_add_u64 v[228:229], v[154:155], 0, s[0:1]
	s_add_i32 m0, s12, 0xe000
	s_nop 0
	global_load_lds_dwordx4 v[228:229], off
	s_waitcnt vmcnt(8)
	s_waitcnt lgkmcnt(0)
	s_barrier
	s_setprio 1
	v_mfma_f32_16x16x32_bf16 v[144:147], v[160:163], v[192:195], v[144:147]
	v_mfma_f32_16x16x32_bf16 v[122:125], v[168:171], v[192:195], v[122:125]
	v_mfma_f32_16x16x32_bf16 v[118:121], v[160:163], v[200:203], v[118:121]
	v_mfma_f32_16x16x32_bf16 v[114:117], v[168:171], v[200:203], v[114:117]
	v_mfma_f32_16x16x32_bf16 v[102:105], v[160:163], v[208:211], v[102:105]
	v_mfma_f32_16x16x32_bf16 v[98:101], v[168:171], v[208:211], v[98:101]
	v_mfma_f32_16x16x32_bf16 v[86:89], v[160:163], v[216:219], v[86:89]
	v_mfma_f32_16x16x32_bf16 v[82:85], v[168:171], v[216:219], v[82:85]
	v_mfma_f32_16x16x32_bf16 v[144:147], v[164:167], v[196:199], v[144:147]
	v_mfma_f32_16x16x32_bf16 v[122:125], v[172:175], v[196:199], v[122:125]
	v_mfma_f32_16x16x32_bf16 v[118:121], v[164:167], v[204:207], v[118:121]
	v_mfma_f32_16x16x32_bf16 v[114:117], v[172:175], v[204:207], v[114:117]
	v_mfma_f32_16x16x32_bf16 v[102:105], v[164:167], v[212:215], v[102:105]
	v_mfma_f32_16x16x32_bf16 v[98:101], v[172:175], v[212:215], v[98:101]
	v_mfma_f32_16x16x32_bf16 v[86:89], v[164:167], v[224:227], v[86:89]
	v_mfma_f32_16x16x32_bf16 v[82:85], v[172:175], v[224:227], v[82:85]
	v_mfma_f32_16x16x32_bf16 v[110:113], v[176:179], v[192:195], v[110:113]
	v_mfma_f32_16x16x32_bf16 v[106:109], v[184:187], v[192:195], v[106:109]
	v_mfma_f32_16x16x32_bf16 v[94:97], v[176:179], v[200:203], v[94:97]
	v_mfma_f32_16x16x32_bf16 v[90:93], v[184:187], v[200:203], v[90:93]
	v_mfma_f32_16x16x32_bf16 v[78:81], v[176:179], v[208:211], v[78:81]
	v_mfma_f32_16x16x32_bf16 v[74:77], v[184:187], v[208:211], v[74:77]
	v_mfma_f32_16x16x32_bf16 v[70:73], v[176:179], v[216:219], v[70:73]
	v_mfma_f32_16x16x32_bf16 v[66:69], v[184:187], v[216:219], v[66:69]
	v_mfma_f32_16x16x32_bf16 v[110:113], v[180:183], v[196:199], v[110:113]
	v_mfma_f32_16x16x32_bf16 v[106:109], v[188:191], v[196:199], v[106:109]
	v_mfma_f32_16x16x32_bf16 v[94:97], v[180:183], v[204:207], v[94:97]
	v_mfma_f32_16x16x32_bf16 v[90:93], v[188:191], v[204:207], v[90:93]
	v_mfma_f32_16x16x32_bf16 v[78:81], v[180:183], v[212:215], v[78:81]
	v_mfma_f32_16x16x32_bf16 v[74:77], v[188:191], v[212:215], v[74:77]
	v_mfma_f32_16x16x32_bf16 v[70:73], v[180:183], v[224:227], v[70:73]
	v_mfma_f32_16x16x32_bf16 v[66:69], v[188:191], v[224:227], v[66:69]
	s_setprio 0
	s_barrier
	s_add_i32 s20, s22, s9
	v_lshl_add_u64 v[228:229], s[4:5], 0, v[0:1]
	s_mov_b32 m0, s20
	ds_read_b128 v[192:195], v159 offset:16384
	ds_read_b128 v[196:199], v159 offset:17408
	ds_read_b128 v[200:203], v159 offset:18432
	ds_read_b128 v[204:207], v159 offset:19456
	ds_read_b128 v[208:211], v159 offset:20480
	ds_read_b128 v[212:215], v159 offset:21504
	ds_read_b128 v[216:219], v159 offset:22528
	ds_read_b128 v[224:227], v159 offset:23552
	global_load_lds_dwordx4 v[228:229], off
	s_add_i32 m0, s20, 0x2000
	s_add_u32 s20, s4, 0x80000
	v_lshl_add_u64 v[230:231], s[4:5], 0, v[126:127]
	s_addc_u32 s21, s5, 0
	s_add_i32 s22, s23, s9
	global_load_lds_dwordx4 v[230:231], off
	v_lshl_add_u64 v[232:233], s[20:21], 0, v[0:1]
	s_mov_b32 m0, s22
	v_lshl_add_u64 v[244:245], s[6:7], 0, v[148:149]
	global_load_lds_dwordx4 v[232:233], off
	v_lshl_add_u64 v[232:233], s[20:21], 0, v[126:127]
	s_add_i32 m0, s22, 0x2000
	s_nop 0
	global_load_lds_dwordx4 v[232:233], off
	v_lshl_add_u64 v[232:233], s[6:7], 0, v[150:151]
	s_mov_b32 m0, s12
	s_nop 0
	global_load_lds_dwordx4 v[232:233], off
	s_mov_b32 m0, s13
	s_nop 0
	global_load_lds_dwordx4 v[244:245], off
	s_waitcnt vmcnt(8)
	s_waitcnt lgkmcnt(0)
	s_barrier
; #define PG8_STAGE(bufoff, gbase, voff) do { _Pragma("unroll") for (int _i = 0; _i < 2; ++_i) \
;         __builtin_amdgcn_global_load_lds((const unsigned*)((const char*)(gbase) + (voff)[_i]), (PG8_LAS unsigned*)(lds + (bufoff) + ldsw + _i * 8192), 16, 0, 0); } while (0)
; #define PG8_LDA(dst, b, h) do { _Pragma("unroll") for (int m = 0; m < 4; ++m) _Pragma("unroll") for (int k = 0; k < 2; ++k) dst[m][k] = *(const PG8_LAS bf16x8*)(lds + PG8_SA(b, h) + aoff + m * 2048 + k * 1024); } while (0)
; #define PG8_LDB(dst, b, h) do { _Pragma("unroll") for (int n = 0; n < 2; ++n) _Pragma("unroll") for (int k = 0; k < 2; ++k) dst[n][k] = *(const PG8_LAS bf16x8*)(lds + PG8_SB(b, h) + boff + n * 2048 + k * 1024); } while (0)
; #define PG8_MMA(ai, bj, At, Bt) do { __builtin_amdgcn_s_setprio(1); _Pragma("unroll") for (int m = 0; m < 4; ++m) _Pragma("unroll") for (int n = 0; n < 2; ++n) _Pragma("unroll") for (int k = 0; k < 2; ++k) \
;         acc[ai][bj][m][n] = __builtin_amdgcn_mfma_f32_16x16x32_bf16(Bt[n][k], At[m][k], acc[ai][bj][m][n], 0, 0, 0); __builtin_amdgcn_s_setprio(0); } while (0)
; #define PG8_WAIT_V(n) asm volatile("s_waitcnt vmcnt(" #n ")" ::: "memory")
; #define PG8_WAIT_L(n) asm volatile("s_waitcnt lgkmcnt(" #n ")" ::: "memory")
; #define PG8_BAR __builtin_amdgcn_s_barrier()
; #define PG8_SCHED __builtin_amdgcn_sched_barrier(0)
; template <class Epi, class Sched, bool ALIGN_EPI = false, bool SP2 = false>
; __device__ __forceinline__ void gemm_phase(PG8_LAS unsigned char* lds, const Gemm g, const Sched& S, const Epi& E) {
;     ...
;             PG8_WAIT_V(8); PG8_WAIT_L(0); PG8_BAR; PG8_MMA(1, 0, At, B0); PG8_MMA(1, 1, At, B1); PG8_BAR; PG8_SCHED;
;             PG8_LDB(B0, 1, 0); PG8_LDB(B1, 1, 1); PG8_SCHED; PG8_LDA(At, 1, 0); PG8_STAGE(PG8_SA(0, 1), a2 + hstep, voffA);
;             PG8_WAIT_V(8); PG8_WAIT_L(0); PG8_BAR; PG8_MMA(0, 0, At, B0); PG8_MMA(0, 1, At, B1); PG8_BAR; PG8_SCHED;
	s_setprio 1
	v_mfma_f32_16x16x32_bf16 v[62:65], v[160:163], v[192:195], v[62:65]
	v_mfma_f32_16x16x32_bf16 v[58:61], v[168:171], v[192:195], v[58:61]
	v_mfma_f32_16x16x32_bf16 v[54:57], v[160:163], v[200:203], v[54:57]
	v_mfma_f32_16x16x32_bf16 v[50:53], v[168:171], v[200:203], v[50:53]
	v_mfma_f32_16x16x32_bf16 v[38:41], v[160:163], v[208:211], v[38:41]
	v_mfma_f32_16x16x32_bf16 v[34:37], v[168:171], v[208:211], v[34:37]
	v_mfma_f32_16x16x32_bf16 v[22:25], v[160:163], v[216:219], v[22:25]
	v_mfma_f32_16x16x32_bf16 v[18:21], v[168:171], v[216:219], v[18:21]
	v_mfma_f32_16x16x32_bf16 v[62:65], v[164:167], v[196:199], v[62:65]
	v_mfma_f32_16x16x32_bf16 v[58:61], v[172:175], v[196:199], v[58:61]
	v_mfma_f32_16x16x32_bf16 v[54:57], v[164:167], v[204:207], v[54:57]
	v_mfma_f32_16x16x32_bf16 v[50:53], v[172:175], v[204:207], v[50:53]
	v_mfma_f32_16x16x32_bf16 v[38:41], v[164:167], v[212:215], v[38:41]
	v_mfma_f32_16x16x32_bf16 v[34:37], v[172:175], v[212:215], v[34:37]
	v_mfma_f32_16x16x32_bf16 v[22:25], v[164:167], v[224:227], v[22:25]
	v_mfma_f32_16x16x32_bf16 v[18:21], v[172:175], v[224:227], v[18:21]
	v_mfma_f32_16x16x32_bf16 v[46:49], v[176:179], v[192:195], v[46:49]
	v_mfma_f32_16x16x32_bf16 v[42:45], v[184:187], v[192:195], v[42:45]
	v_mfma_f32_16x16x32_bf16 v[30:33], v[176:179], v[200:203], v[30:33]
	v_mfma_f32_16x16x32_bf16 v[26:29], v[184:187], v[200:203], v[26:29]
	v_mfma_f32_16x16x32_bf16 v[14:17], v[176:179], v[208:211], v[14:17]
	v_mfma_f32_16x16x32_bf16 v[10:13], v[184:187], v[208:211], v[10:13]
	v_mfma_f32_16x16x32_bf16 v[6:9], v[176:179], v[216:219], v[6:9]
	v_mfma_f32_16x16x32_bf16 v[2:5], v[184:187], v[216:219], v[2:5]
	v_mfma_f32_16x16x32_bf16 v[46:49], v[180:183], v[196:199], v[46:49]
	v_mfma_f32_16x16x32_bf16 v[42:45], v[188:191], v[196:199], v[42:45]
	v_mfma_f32_16x16x32_bf16 v[30:33], v[180:183], v[204:207], v[30:33]
	v_mfma_f32_16x16x32_bf16 v[26:29], v[188:191], v[204:207], v[26:29]
	v_mfma_f32_16x16x32_bf16 v[14:17], v[180:183], v[212:215], v[14:17]
	v_mfma_f32_16x16x32_bf16 v[10:13], v[188:191], v[212:215], v[10:13]
	v_mfma_f32_16x16x32_bf16 v[6:9], v[180:183], v[224:227], v[6:9]
	v_mfma_f32_16x16x32_bf16 v[2:5], v[188:191], v[224:227], v[2:5]
	s_setprio 0
	s_barrier
	s_add_i32 s20, 0, 0x18000
	s_add_i32 s21, 0, 0x1c000
	v_add_u32_e32 v172, s20, v158
	v_add_u32_e32 v188, s21, v158
	ds_read_b128 v[160:163], v172
	ds_read_b128 v[164:167], v172 offset:1024
	ds_read_b128 v[168:171], v172 offset:2048
	ds_read_b128 v[172:175], v172 offset:3072
	ds_read_b128 v[176:179], v188
	ds_read_b128 v[180:183], v188 offset:1024
	ds_read_b128 v[184:187], v188 offset:2048
	ds_read_b128 v[188:191], v188 offset:3072
	s_add_u32 s6, s6, 0x80000
	s_addc_u32 s7, s7, 0
	s_mov_b32 m0, s14
	v_lshl_add_u64 v[246:247], s[6:7], 0, v[150:151]
	ds_read_b128 v[192:195], v159 offset:32768
	ds_read_b128 v[196:199], v159 offset:33792
	ds_read_b128 v[200:203], v159 offset:34816
	ds_read_b128 v[204:207], v159 offset:35840
	ds_read_b128 v[208:211], v159 offset:36864
	ds_read_b128 v[212:215], v159 offset:37888
	ds_read_b128 v[216:219], v159 offset:38912
	ds_read_b128 v[224:227], v159 offset:39936
	global_load_lds_dwordx4 v[246:247], off
	v_lshl_add_u64 v[246:247], s[6:7], 0, v[148:149]
	s_mov_b32 m0, s15
	s_nop 0
	global_load_lds_dwordx4 v[246:247], off
	s_waitcnt vmcnt(8)
	s_waitcnt lgkmcnt(0)
	s_barrier
	s_setprio 1
	v_mfma_f32_16x16x32_bf16 v[144:147], v[160:163], v[192:195], v[144:147]
	v_mfma_f32_16x16x32_bf16 v[122:125], v[168:171], v[192:195], v[122:125]
	v_mfma_f32_16x16x32_bf16 v[118:121], v[160:163], v[200:203], v[118:121]
	v_mfma_f32_16x16x32_bf16 v[114:117], v[168:171], v[200:203], v[114:117]
	v_mfma_f32_16x16x32_bf16 v[102:105], v[160:163], v[208:211], v[102:105]
	v_mfma_f32_16x16x32_bf16 v[98:101], v[168:171], v[208:211], v[98:101]
	v_mfma_f32_16x16x32_bf16 v[86:89], v[160:163], v[216:219], v[86:89]
	v_mfma_f32_16x16x32_bf16 v[82:85], v[168:171], v[216:219], v[82:85]
	v_mfma_f32_16x16x32_bf16 v[144:147], v[164:167], v[196:199], v[144:147]
	v_mfma_f32_16x16x32_bf16 v[122:125], v[172:175], v[196:199], v[122:125]
	v_mfma_f32_16x16x32_bf16 v[118:121], v[164:167], v[204:207], v[118:121]
	v_mfma_f32_16x16x32_bf16 v[114:117], v[172:175], v[204:207], v[114:117]
	v_mfma_f32_16x16x32_bf16 v[102:105], v[164:167], v[212:215], v[102:105]
	v_mfma_f32_16x16x32_bf16 v[98:101], v[172:175], v[212:215], v[98:101]
	v_mfma_f32_16x16x32_bf16 v[86:89], v[164:167], v[224:227], v[86:89]
	v_mfma_f32_16x16x32_bf16 v[82:85], v[172:175], v[224:227], v[82:85]
	v_mfma_f32_16x16x32_bf16 v[110:113], v[176:179], v[192:195], v[110:113]
	v_mfma_f32_16x16x32_bf16 v[106:109], v[184:187], v[192:195], v[106:109]
	v_mfma_f32_16x16x32_bf16 v[94:97], v[176:179], v[200:203], v[94:97]
	v_mfma_f32_16x16x32_bf16 v[90:93], v[184:187], v[200:203], v[90:93]
	v_mfma_f32_16x16x32_bf16 v[78:81], v[176:179], v[208:211], v[78:81]
	v_mfma_f32_16x16x32_bf16 v[74:77], v[184:187], v[208:211], v[74:77]
	v_mfma_f32_16x16x32_bf16 v[70:73], v[176:179], v[216:219], v[70:73]
	v_mfma_f32_16x16x32_bf16 v[66:69], v[184:187], v[216:219], v[66:69]
	v_mfma_f32_16x16x32_bf16 v[110:113], v[180:183], v[196:199], v[110:113]
	v_mfma_f32_16x16x32_bf16 v[106:109], v[188:191], v[196:199], v[106:109]
	v_mfma_f32_16x16x32_bf16 v[94:97], v[180:183], v[204:207], v[94:97]
	v_mfma_f32_16x16x32_bf16 v[90:93], v[188:191], v[204:207], v[90:93]
	v_mfma_f32_16x16x32_bf16 v[78:81], v[180:183], v[212:215], v[78:81]
	v_mfma_f32_16x16x32_bf16 v[74:77], v[188:191], v[212:215], v[74:77]
	v_mfma_f32_16x16x32_bf16 v[70:73], v[180:183], v[224:227], v[70:73]
	v_mfma_f32_16x16x32_bf16 v[66:69], v[188:191], v[224:227], v[66:69]
	s_setprio 0
	s_barrier
; #define PG8_STAGE(bufoff, gbase, voff) do { _Pragma("unroll") for (int _i = 0; _i < 2; ++_i) \
;         __builtin_amdgcn_global_load_lds((const unsigned*)((const char*)(gbase) + (voff)[_i]), (PG8_LAS unsigned*)(lds + (bufoff) + ldsw + _i * 8192), 16, 0, 0); } while (0)
; #define PG8_LDA(dst, b, h) do { _Pragma("unroll") for (int m = 0; m < 4; ++m) _Pragma("unroll") for (int k = 0; k < 2; ++k) dst[m][k] = *(const PG8_LAS bf16x8*)(lds + PG8_SA(b, h) + aoff + m * 2048 + k * 1024); } while (0)
; #define PG8_MMA(ai, bj, At, Bt) do { __builtin_amdgcn_s_setprio(1); _Pragma("unroll") for (int m = 0; m < 4; ++m) _Pragma("unroll") for (int n = 0; n < 2; ++n) _Pragma("unroll") for (int k = 0; k < 2; ++k) \
;         acc[ai][bj][m][n] = __builtin_amdgcn_mfma_f32_16x16x32_bf16(Bt[n][k], At[m][k], acc[ai][bj][m][n], 0, 0, 0); __builtin_amdgcn_s_setprio(0); } while (0)
; #define PG8_WAIT_V(n) asm volatile("s_waitcnt vmcnt(" #n ")" ::: "memory")
; #define PG8_WAIT_L(n) asm volatile("s_waitcnt lgkmcnt(" #n ")" ::: "memory")
; #define PG8_BAR __builtin_amdgcn_s_barrier()
; #define PG8_SCHED __builtin_amdgcn_sched_barrier(0)
; template <class Epi, class Sched, bool ALIGN_EPI = false, bool SP2 = false>
; __device__ __forceinline__ void gemm_phase(PG8_LAS unsigned char* lds, const Gemm g, const Sched& S, const Epi& E) {
;     ...
;             PG8_LDA(At, 1, 1); PG8_STAGE(PG8_SB(1, 0), b3, voffB); PG8_STAGE(PG8_SB(1, 1), b3 + hstep, voffB); PG8_STAGE(PG8_SA(1, 0), a3, voffA);
;             PG8_WAIT_V(8); PG8_WAIT_L(0); PG8_BAR; PG8_MMA(1, 0, At, B0); PG8_MMA(1, 1, At, B1); PG8_BAR; PG8_SCHED;
	s_add_i32 s6, s20, s9
	v_lshl_add_u64 v[228:229], v[228:229], 0, s[64:65]
	s_mov_b32 m0, s6
	ds_read_b128 v[192:195], v159 offset:49152
	ds_read_b128 v[196:199], v159 offset:50176
	ds_read_b128 v[200:203], v159 offset:51200
	ds_read_b128 v[204:207], v159 offset:52224
	ds_read_b128 v[208:211], v159 offset:53248
	ds_read_b128 v[212:215], v159 offset:54272
	ds_read_b128 v[216:219], v159 offset:55296
	ds_read_b128 v[224:227], v159 offset:56320
	global_load_lds_dwordx4 v[228:229], off
	s_add_i32 m0, s6, 0x2000
	s_add_u32 s4, s4, 0x80080
	v_lshl_add_u64 v[228:229], v[230:231], 0, s[64:65]
	s_addc_u32 s5, s5, 0
	s_add_i32 s6, s21, s9
	global_load_lds_dwordx4 v[228:229], off
	v_lshl_add_u64 v[228:229], s[4:5], 0, v[0:1]
	s_mov_b32 m0, s6
	s_nop 0
	global_load_lds_dwordx4 v[228:229], off
	v_lshl_add_u64 v[228:229], s[4:5], 0, v[126:127]
	s_add_i32 m0, s6, 0x2000
	s_nop 0
	global_load_lds_dwordx4 v[228:229], off
	v_lshl_add_u64 v[228:229], v[232:233], 0, s[64:65]
	s_mov_b32 m0, s17
	s_nop 0
	global_load_lds_dwordx4 v[228:229], off
	v_lshl_add_u64 v[228:229], v[244:245], 0, s[64:65]
	s_mov_b32 m0, s18
	s_nop 0
	global_load_lds_dwordx4 v[228:229], off
	s_waitcnt vmcnt(8)
	s_waitcnt lgkmcnt(0)
	s_barrier
	s_setprio 1
	v_mfma_f32_16x16x32_bf16 v[62:65], v[160:163], v[192:195], v[62:65]
	v_mfma_f32_16x16x32_bf16 v[58:61], v[168:171], v[192:195], v[58:61]
	v_mfma_f32_16x16x32_bf16 v[54:57], v[160:163], v[200:203], v[54:57]
	v_mfma_f32_16x16x32_bf16 v[50:53], v[168:171], v[200:203], v[50:53]
	v_mfma_f32_16x16x32_bf16 v[38:41], v[160:163], v[208:211], v[38:41]
	v_mfma_f32_16x16x32_bf16 v[34:37], v[168:171], v[208:211], v[34:37]
	v_mfma_f32_16x16x32_bf16 v[22:25], v[160:163], v[216:219], v[22:25]
	v_mfma_f32_16x16x32_bf16 v[18:21], v[168:171], v[216:219], v[18:21]
	v_mfma_f32_16x16x32_bf16 v[62:65], v[164:167], v[196:199], v[62:65]
	v_mfma_f32_16x16x32_bf16 v[58:61], v[172:175], v[196:199], v[58:61]
	v_mfma_f32_16x16x32_bf16 v[54:57], v[164:167], v[204:207], v[54:57]
	v_mfma_f32_16x16x32_bf16 v[50:53], v[172:175], v[204:207], v[50:53]
	v_mfma_f32_16x16x32_bf16 v[38:41], v[164:167], v[212:215], v[38:41]
	v_mfma_f32_16x16x32_bf16 v[34:37], v[172:175], v[212:215], v[34:37]
	v_mfma_f32_16x16x32_bf16 v[22:25], v[164:167], v[224:227], v[22:25]
	v_mfma_f32_16x16x32_bf16 v[18:21], v[172:175], v[224:227], v[18:21]
	v_mfma_f32_16x16x32_bf16 v[46:49], v[176:179], v[192:195], v[46:49]
	v_mfma_f32_16x16x32_bf16 v[42:45], v[184:187], v[192:195], v[42:45]
	v_mfma_f32_16x16x32_bf16 v[30:33], v[176:179], v[200:203], v[30:33]
	v_mfma_f32_16x16x32_bf16 v[26:29], v[184:187], v[200:203], v[26:29]
	v_mfma_f32_16x16x32_bf16 v[14:17], v[176:179], v[208:211], v[14:17]
	v_mfma_f32_16x16x32_bf16 v[10:13], v[184:187], v[208:211], v[10:13]
	v_mfma_f32_16x16x32_bf16 v[6:9], v[176:179], v[216:219], v[6:9]
	v_mfma_f32_16x16x32_bf16 v[2:5], v[184:187], v[216:219], v[2:5]
	v_mfma_f32_16x16x32_bf16 v[46:49], v[180:183], v[196:199], v[46:49]
	v_mfma_f32_16x16x32_bf16 v[42:45], v[188:191], v[196:199], v[42:45]
	v_mfma_f32_16x16x32_bf16 v[30:33], v[180:183], v[204:207], v[30:33]
	v_mfma_f32_16x16x32_bf16 v[26:29], v[188:191], v[204:207], v[26:29]
	v_mfma_f32_16x16x32_bf16 v[14:17], v[180:183], v[212:215], v[14:17]
	v_mfma_f32_16x16x32_bf16 v[10:13], v[188:191], v[212:215], v[10:13]
	v_mfma_f32_16x16x32_bf16 v[6:9], v[180:183], v[224:227], v[6:9]
	v_mfma_f32_16x16x32_bf16 v[2:5], v[188:191], v[224:227], v[2:5]
	s_setprio 0
	s_barrier
	s_add_i32 s19, s19, 2
	s_add_u32 s0, s0, 0x100
	s_addc_u32 s1, s1, 0
	s_cmp_gt_u32 s19, 29
	s_cbranch_scc0 .LBB0_307
	s_cmpk_lt_u32 s8, 0x100
	s_cbranch_scc0 .LBB0_310
	s_barrier

;     __device__ __forceinline__ bool next(int i, Unit& u) const { if (i > 0 || c < first) return false; const int idx = c - first; u.pm = idx % nM; u.pn = idx / nM; return true; }
; #define PG8_STAGE(bufoff, gbase, voff) do { _Pragma("unroll") for (int _i = 0; _i < 2; ++_i) \
;         __builtin_amdgcn_global_load_lds((const unsigned*)((const char*)(gbase) + (voff)[_i]), (PG8_LAS unsigned*)(lds + (bufoff) + ldsw + _i * 8192), 16, 0, 0); } while (0)
; #define PG8_LDA(dst, b, h) do { _Pragma("unroll") for (int m = 0; m < 4; ++m) _Pragma("unroll") for (int k = 0; k < 2; ++k) dst[m][k] = *(const PG8_LAS bf16x8*)(lds + PG8_SA(b, h) + aoff + m * 2048 + k * 1024); } while (0)
; #define PG8_WAIT_V(n) asm volatile("s_waitcnt vmcnt(" #n ")" ::: "memory")
; #define PG8_WAIT_L(n) asm volatile("s_waitcnt lgkmcnt(" #n ")" ::: "memory")
; #define PG8_BAR __builtin_amdgcn_s_barrier()
; template <class Epi, class Sched, bool ALIGN_EPI = false, bool SP2 = false>
; __device__ __forceinline__ void gemm_phase(PG8_LAS unsigned char* lds, const Gemm g, const Sched& S, const Epi& E) {
;     ...
;         const bool has_next = S.next(ui + 1, nxt);
;         const char* nA = has_next ? (const char*)g.A + (size_t)nxt.pm * tstep : cA; const char* nB = has_next ? (const char*)g.Bt + (size_t)nxt.pn * tstep : cB;
;         for (int t = 0; t < nt; t += 2) {
;             if constexpr (Epi::HAS_MID) { if (t == Epi::MID0 || t == Epi::MID1) E.mid(acc, cur, wr, wc, fr, fq, t == Epi::MID0 ? 0 : 1); }
;             const bool last = (t == nt - 2);
;             const char* a1 = cA + (size_t)(t + 1) * kstep;
;             const char* a2 = last ? nA : cA + (size_t)(t + 2) * kstep; const char* b2 = last ? nB : cB + (size_t)(t + 2) * kstep;
;             const char* a3 = a2 + kstep; const char* b3 = b2 + kstep;
;             if (last && has_next) S.a_ready(nxt);
;             if constexpr (SP2) {
;             PG8_LDB(B0, 0, 0); PG8_LDB(B1, 0, 1); PG8_SCHED; PG8_LDA(At, 0, 0); PG8_STAGE(PG8_SA(1, 1), a1 + hstep, voffA);
;             PG8_WAIT_V(8); PG8_WAIT_L(0); PG8_BAR; PG8_MMA(0, 0, At, B0); PG8_MMA(0, 1, At, B1); PG8_BAR; PG8_SCHED;
;             PG8_LDA(At, 0, 1); PG8_STAGE(PG8_SB(0, 0), b2, voffB); PG8_STAGE(PG8_SB(0, 1), b2 + hstep, voffB); PG8_STAGE(PG8_SA(0, 0), a2, voffA);
;             PG8_WAIT_V(8); PG8_WAIT_L(0); PG8_BAR; PG8_MMA(1, 0, At, B0); PG8_MMA(1, 1, At, B1); PG8_BAR; PG8_SCHED;
.LBB0_733:
	s_add_u32 s22, s18, s20
	s_addc_u32 s23, s19, s21
	s_add_u32 s22, s22, 0x100
	s_addc_u32 s23, s23, 0
	s_add_u32 s26, s86, s20
	s_addc_u32 s27, s87, s21
	s_add_i32 s40, 0, 0x10000
	s_cmpk_eq_i32 s20, 0xf00
	s_cselect_b32 s25, s13, s23
	s_cselect_b32 s24, s82, s22
	s_cselect_b32 s23, s9, s27
	s_cselect_b32 s22, s83, s26
	s_add_i32 s41, 0, 0x14000
	v_add_u32_e32 v160, s40, v245
	v_add_u32_e32 v176, s41, v245
	ds_read_b128 v[148:151], v160
	ds_read_b128 v[152:155], v160 offset:1024
	ds_read_b128 v[156:159], v160 offset:2048
	ds_read_b128 v[160:163], v160 offset:3072
	ds_read_b128 v[164:167], v176
	ds_read_b128 v[168:171], v176 offset:1024
	ds_read_b128 v[172:175], v176 offset:2048
	ds_read_b128 v[176:179], v176 offset:3072
	v_lshl_add_u64 v[232:233], v[228:229], 0, s[20:21]
	s_add_i32 m0, s31, 0xc000
	ds_read_b128 v[180:183], v247
	ds_read_b128 v[184:187], v247 offset:1024
	ds_read_b128 v[188:191], v247 offset:2048
	ds_read_b128 v[192:195], v247 offset:3072
	ds_read_b128 v[196:199], v247 offset:4096
	ds_read_b128 v[200:203], v247 offset:5120
	ds_read_b128 v[204:207], v247 offset:6144
	ds_read_b128 v[208:211], v247 offset:7168
	global_load_lds_dwordx4 v[232:233], off
	v_lshl_add_u64 v[232:233], v[230:231], 0, s[20:21]
	s_add_i32 m0, s31, 0xe000
	s_nop 0
	global_load_lds_dwordx4 v[232:233], off
	s_waitcnt vmcnt(8)
	s_waitcnt lgkmcnt(0)
	s_barrier
	s_setprio 1
	v_mfma_f32_16x16x32_bf16 v[144:147], v[148:151], v[180:183], v[144:147]
	v_mfma_f32_16x16x32_bf16 v[122:125], v[156:159], v[180:183], v[122:125]
	v_mfma_f32_16x16x32_bf16 v[110:113], v[148:151], v[188:191], v[110:113]
	v_mfma_f32_16x16x32_bf16 v[106:109], v[156:159], v[188:191], v[106:109]
	v_mfma_f32_16x16x32_bf16 v[94:97], v[148:151], v[196:199], v[94:97]
	v_mfma_f32_16x16x32_bf16 v[90:93], v[156:159], v[196:199], v[90:93]
	v_mfma_f32_16x16x32_bf16 v[78:81], v[148:151], v[204:207], v[78:81]
	v_mfma_f32_16x16x32_bf16 v[74:77], v[156:159], v[204:207], v[74:77]
	v_mfma_f32_16x16x32_bf16 v[144:147], v[152:155], v[184:187], v[144:147]
	v_mfma_f32_16x16x32_bf16 v[122:125], v[160:163], v[184:187], v[122:125]
	v_mfma_f32_16x16x32_bf16 v[110:113], v[152:155], v[192:195], v[110:113]
	v_mfma_f32_16x16x32_bf16 v[106:109], v[160:163], v[192:195], v[106:109]
	v_mfma_f32_16x16x32_bf16 v[94:97], v[152:155], v[200:203], v[94:97]
	v_mfma_f32_16x16x32_bf16 v[90:93], v[160:163], v[200:203], v[90:93]
	v_mfma_f32_16x16x32_bf16 v[78:81], v[152:155], v[208:211], v[78:81]
	v_mfma_f32_16x16x32_bf16 v[74:77], v[160:163], v[208:211], v[74:77]
	v_mfma_f32_16x16x32_bf16 v[118:121], v[164:167], v[180:183], v[118:121]
	v_mfma_f32_16x16x32_bf16 v[114:117], v[172:175], v[180:183], v[114:117]
	v_mfma_f32_16x16x32_bf16 v[102:105], v[164:167], v[188:191], v[102:105]
	v_mfma_f32_16x16x32_bf16 v[98:101], v[172:175], v[188:191], v[98:101]
	v_mfma_f32_16x16x32_bf16 v[86:89], v[164:167], v[196:199], v[86:89]
	v_mfma_f32_16x16x32_bf16 v[82:85], v[172:175], v[196:199], v[82:85]
	v_mfma_f32_16x16x32_bf16 v[70:73], v[164:167], v[204:207], v[70:73]
	v_mfma_f32_16x16x32_bf16 v[66:69], v[172:175], v[204:207], v[66:69]
	v_mfma_f32_16x16x32_bf16 v[118:121], v[168:171], v[184:187], v[118:121]
	v_mfma_f32_16x16x32_bf16 v[114:117], v[176:179], v[184:187], v[114:117]
	v_mfma_f32_16x16x32_bf16 v[102:105], v[168:171], v[192:195], v[102:105]
	v_mfma_f32_16x16x32_bf16 v[98:101], v[176:179], v[192:195], v[98:101]
	v_mfma_f32_16x16x32_bf16 v[86:89], v[168:171], v[200:203], v[86:89]
	v_mfma_f32_16x16x32_bf16 v[82:85], v[176:179], v[200:203], v[82:85]
	v_mfma_f32_16x16x32_bf16 v[70:73], v[168:171], v[208:211], v[70:73]
	v_mfma_f32_16x16x32_bf16 v[66:69], v[176:179], v[208:211], v[66:69]
	s_setprio 0
	s_barrier
	s_add_i32 s26, s40, s30
	v_lshl_add_u64 v[232:233], s[22:23], 0, v[0:1]
	s_mov_b32 m0, s26
	ds_read_b128 v[180:183], v247 offset:16384
	ds_read_b128 v[184:187], v247 offset:17408
	ds_read_b128 v[188:191], v247 offset:18432
	ds_read_b128 v[192:195], v247 offset:19456
	ds_read_b128 v[196:199], v247 offset:20480
	ds_read_b128 v[200:203], v247 offset:21504
	ds_read_b128 v[204:207], v247 offset:22528
	ds_read_b128 v[208:211], v247 offset:23552
	global_load_lds_dwordx4 v[232:233], off
	s_add_i32 m0, s26, 0x2000
	s_add_u32 s26, s22, 0x80000
	v_lshl_add_u64 v[248:249], s[22:23], 0, v[126:127]
	s_addc_u32 s27, s23, 0
	s_add_i32 s40, s41, s30
	global_load_lds_dwordx4 v[248:249], off
	v_lshl_add_u64 v[250:251], s[26:27], 0, v[0:1]
	s_mov_b32 m0, s40
	v_lshl_add_u64 v[220:221], s[24:25], 0, v[212:213]
	global_load_lds_dwordx4 v[250:251], off
	v_lshl_add_u64 v[250:251], s[26:27], 0, v[126:127]
	s_add_i32 m0, s40, 0x2000
	s_nop 0
	global_load_lds_dwordx4 v[250:251], off
	v_lshl_add_u64 v[250:251], s[24:25], 0, v[214:215]
	s_mov_b32 m0, s31
	s_nop 0
	global_load_lds_dwordx4 v[250:251], off
	s_mov_b32 m0, s34
	s_nop 0
	global_load_lds_dwordx4 v[220:221], off
	s_waitcnt vmcnt(8)
	s_waitcnt lgkmcnt(0)
	s_barrier
; #define PG8_STAGE(bufoff, gbase, voff) do { _Pragma("unroll") for (int _i = 0; _i < 2; ++_i) \
;         __builtin_amdgcn_global_load_lds((const unsigned*)((const char*)(gbase) + (voff)[_i]), (PG8_LAS unsigned*)(lds + (bufoff) + ldsw + _i * 8192), 16, 0, 0); } while (0)
; #define PG8_LDA(dst, b, h) do { _Pragma("unroll") for (int m = 0; m < 4; ++m) _Pragma("unroll") for (int k = 0; k < 2; ++k) dst[m][k] = *(const PG8_LAS bf16x8*)(lds + PG8_SA(b, h) + aoff + m * 2048 + k * 1024); } while (0)
; #define PG8_LDB(dst, b, h) do { _Pragma("unroll") for (int n = 0; n < 2; ++n) _Pragma("unroll") for (int k = 0; k < 2; ++k) dst[n][k] = *(const PG8_LAS bf16x8*)(lds + PG8_SB(b, h) + boff + n * 2048 + k * 1024); } while (0)
; #define PG8_MMA(ai, bj, At, Bt) do { __builtin_amdgcn_s_setprio(1); _Pragma("unroll") for (int m = 0; m < 4; ++m) _Pragma("unroll") for (int n = 0; n < 2; ++n) _Pragma("unroll") for (int k = 0; k < 2; ++k) \
;         acc[ai][bj][m][n] = __builtin_amdgcn_mfma_f32_16x16x32_bf16(Bt[n][k], At[m][k], acc[ai][bj][m][n], 0, 0, 0); __builtin_amdgcn_s_setprio(0); } while (0)
; #define PG8_WAIT_V(n) asm volatile("s_waitcnt vmcnt(" #n ")" ::: "memory")
; #define PG8_WAIT_L(n) asm volatile("s_waitcnt lgkmcnt(" #n ")" ::: "memory")
; #define PG8_BAR __builtin_amdgcn_s_barrier()
; #define PG8_SCHED __builtin_amdgcn_sched_barrier(0)
; template <class Epi, class Sched, bool ALIGN_EPI = false, bool SP2 = false>
; __device__ __forceinline__ void gemm_phase(PG8_LAS unsigned char* lds, const Gemm g, const Sched& S, const Epi& E) {
;     ...
;             PG8_WAIT_V(8); PG8_WAIT_L(0); PG8_BAR; PG8_MMA(1, 0, At, B0); PG8_MMA(1, 1, At, B1); PG8_BAR; PG8_SCHED;
;             PG8_LDB(B0, 1, 0); PG8_LDB(B1, 1, 1); PG8_SCHED; PG8_LDA(At, 1, 0); PG8_STAGE(PG8_SA(0, 1), a2 + hstep, voffA);
;             PG8_WAIT_V(8); PG8_WAIT_L(0); PG8_BAR; PG8_MMA(0, 0, At, B0); PG8_MMA(0, 1, At, B1); PG8_BAR; PG8_SCHED;
	s_setprio 1
	v_mfma_f32_16x16x32_bf16 v[62:65], v[148:151], v[180:183], v[62:65]
	v_mfma_f32_16x16x32_bf16 v[58:61], v[156:159], v[180:183], v[58:61]
	v_mfma_f32_16x16x32_bf16 v[46:49], v[148:151], v[188:191], v[46:49]
	v_mfma_f32_16x16x32_bf16 v[42:45], v[156:159], v[188:191], v[42:45]
	v_mfma_f32_16x16x32_bf16 v[30:33], v[148:151], v[196:199], v[30:33]
	v_mfma_f32_16x16x32_bf16 v[26:29], v[156:159], v[196:199], v[26:29]
	v_mfma_f32_16x16x32_bf16 v[14:17], v[148:151], v[204:207], v[14:17]
	v_mfma_f32_16x16x32_bf16 v[10:13], v[156:159], v[204:207], v[10:13]
	v_mfma_f32_16x16x32_bf16 v[62:65], v[152:155], v[184:187], v[62:65]
	v_mfma_f32_16x16x32_bf16 v[58:61], v[160:163], v[184:187], v[58:61]
	v_mfma_f32_16x16x32_bf16 v[46:49], v[152:155], v[192:195], v[46:49]
	v_mfma_f32_16x16x32_bf16 v[42:45], v[160:163], v[192:195], v[42:45]
	v_mfma_f32_16x16x32_bf16 v[30:33], v[152:155], v[200:203], v[30:33]
	v_mfma_f32_16x16x32_bf16 v[26:29], v[160:163], v[200:203], v[26:29]
	v_mfma_f32_16x16x32_bf16 v[14:17], v[152:155], v[208:211], v[14:17]
	v_mfma_f32_16x16x32_bf16 v[10:13], v[160:163], v[208:211], v[10:13]
	v_mfma_f32_16x16x32_bf16 v[54:57], v[164:167], v[180:183], v[54:57]
	v_mfma_f32_16x16x32_bf16 v[50:53], v[172:175], v[180:183], v[50:53]
	v_mfma_f32_16x16x32_bf16 v[38:41], v[164:167], v[188:191], v[38:41]
	v_mfma_f32_16x16x32_bf16 v[34:37], v[172:175], v[188:191], v[34:37]
	v_mfma_f32_16x16x32_bf16 v[22:25], v[164:167], v[196:199], v[22:25]
	v_mfma_f32_16x16x32_bf16 v[18:21], v[172:175], v[196:199], v[18:21]
	v_mfma_f32_16x16x32_bf16 v[6:9], v[164:167], v[204:207], v[6:9]
	v_mfma_f32_16x16x32_bf16 v[2:5], v[172:175], v[204:207], v[2:5]
	v_mfma_f32_16x16x32_bf16 v[54:57], v[168:171], v[184:187], v[54:57]
	v_mfma_f32_16x16x32_bf16 v[50:53], v[176:179], v[184:187], v[50:53]
	v_mfma_f32_16x16x32_bf16 v[38:41], v[168:171], v[192:195], v[38:41]
	v_mfma_f32_16x16x32_bf16 v[34:37], v[176:179], v[192:195], v[34:37]
	v_mfma_f32_16x16x32_bf16 v[22:25], v[168:171], v[200:203], v[22:25]
	v_mfma_f32_16x16x32_bf16 v[18:21], v[176:179], v[200:203], v[18:21]
	v_mfma_f32_16x16x32_bf16 v[6:9], v[168:171], v[208:211], v[6:9]
	v_mfma_f32_16x16x32_bf16 v[2:5], v[176:179], v[208:211], v[2:5]
	s_setprio 0
	s_barrier
	s_add_i32 s26, 0, 0x18000
	s_add_i32 s27, 0, 0x1c000
	v_add_u32_e32 v160, s26, v245
	v_add_u32_e32 v176, s27, v245
	ds_read_b128 v[148:151], v160
	ds_read_b128 v[152:155], v160 offset:1024
	ds_read_b128 v[156:159], v160 offset:2048
	ds_read_b128 v[160:163], v160 offset:3072
	ds_read_b128 v[164:167], v176
	ds_read_b128 v[168:171], v176 offset:1024
	ds_read_b128 v[172:175], v176 offset:2048
	ds_read_b128 v[176:179], v176 offset:3072
	s_add_u32 s24, s24, 0x80000
	s_addc_u32 s25, s25, 0
	s_mov_b32 m0, s35
	v_lshl_add_u64 v[222:223], s[24:25], 0, v[214:215]
	ds_read_b128 v[180:183], v247 offset:32768
	ds_read_b128 v[184:187], v247 offset:33792
	ds_read_b128 v[188:191], v247 offset:34816
	ds_read_b128 v[192:195], v247 offset:35840
	ds_read_b128 v[196:199], v247 offset:36864
	ds_read_b128 v[200:203], v247 offset:37888
	ds_read_b128 v[204:207], v247 offset:38912
	ds_read_b128 v[208:211], v247 offset:39936
	global_load_lds_dwordx4 v[222:223], off
	v_lshl_add_u64 v[222:223], s[24:25], 0, v[212:213]
	s_mov_b32 m0, s36
	s_nop 0
	global_load_lds_dwordx4 v[222:223], off
	s_waitcnt vmcnt(8)
	s_waitcnt lgkmcnt(0)
	s_barrier
	s_setprio 1
	v_mfma_f32_16x16x32_bf16 v[144:147], v[148:151], v[180:183], v[144:147]
	v_mfma_f32_16x16x32_bf16 v[122:125], v[156:159], v[180:183], v[122:125]
	v_mfma_f32_16x16x32_bf16 v[110:113], v[148:151], v[188:191], v[110:113]
	v_mfma_f32_16x16x32_bf16 v[106:109], v[156:159], v[188:191], v[106:109]
	v_mfma_f32_16x16x32_bf16 v[94:97], v[148:151], v[196:199], v[94:97]
	v_mfma_f32_16x16x32_bf16 v[90:93], v[156:159], v[196:199], v[90:93]
	v_mfma_f32_16x16x32_bf16 v[78:81], v[148:151], v[204:207], v[78:81]
	v_mfma_f32_16x16x32_bf16 v[74:77], v[156:159], v[204:207], v[74:77]
	v_mfma_f32_16x16x32_bf16 v[144:147], v[152:155], v[184:187], v[144:147]
	v_mfma_f32_16x16x32_bf16 v[122:125], v[160:163], v[184:187], v[122:125]
	v_mfma_f32_16x16x32_bf16 v[110:113], v[152:155], v[192:195], v[110:113]
	v_mfma_f32_16x16x32_bf16 v[106:109], v[160:163], v[192:195], v[106:109]
	v_mfma_f32_16x16x32_bf16 v[94:97], v[152:155], v[200:203], v[94:97]
	v_mfma_f32_16x16x32_bf16 v[90:93], v[160:163], v[200:203], v[90:93]
	v_mfma_f32_16x16x32_bf16 v[78:81], v[152:155], v[208:211], v[78:81]
	v_mfma_f32_16x16x32_bf16 v[74:77], v[160:163], v[208:211], v[74:77]
	v_mfma_f32_16x16x32_bf16 v[118:121], v[164:167], v[180:183], v[118:121]
	v_mfma_f32_16x16x32_bf16 v[114:117], v[172:175], v[180:183], v[114:117]
	v_mfma_f32_16x16x32_bf16 v[102:105], v[164:167], v[188:191], v[102:105]
	v_mfma_f32_16x16x32_bf16 v[98:101], v[172:175], v[188:191], v[98:101]
	v_mfma_f32_16x16x32_bf16 v[86:89], v[164:167], v[196:199], v[86:89]
	v_mfma_f32_16x16x32_bf16 v[82:85], v[172:175], v[196:199], v[82:85]
	v_mfma_f32_16x16x32_bf16 v[70:73], v[164:167], v[204:207], v[70:73]
	v_mfma_f32_16x16x32_bf16 v[66:69], v[172:175], v[204:207], v[66:69]
	v_mfma_f32_16x16x32_bf16 v[118:121], v[168:171], v[184:187], v[118:121]
	v_mfma_f32_16x16x32_bf16 v[114:117], v[176:179], v[184:187], v[114:117]
	v_mfma_f32_16x16x32_bf16 v[102:105], v[168:171], v[192:195], v[102:105]
	v_mfma_f32_16x16x32_bf16 v[98:101], v[176:179], v[192:195], v[98:101]
	v_mfma_f32_16x16x32_bf16 v[86:89], v[168:171], v[200:203], v[86:89]
	v_mfma_f32_16x16x32_bf16 v[82:85], v[176:179], v[200:203], v[82:85]
	v_mfma_f32_16x16x32_bf16 v[70:73], v[168:171], v[208:211], v[70:73]
	v_mfma_f32_16x16x32_bf16 v[66:69], v[176:179], v[208:211], v[66:69]
	s_setprio 0
	s_barrier
; #define PG8_STAGE(bufoff, gbase, voff) do { _Pragma("unroll") for (int _i = 0; _i < 2; ++_i) \
;         __builtin_amdgcn_global_load_lds((const unsigned*)((const char*)(gbase) + (voff)[_i]), (PG8_LAS unsigned*)(lds + (bufoff) + ldsw + _i * 8192), 16, 0, 0); } while (0)
; #define PG8_LDA(dst, b, h) do { _Pragma("unroll") for (int m = 0; m < 4; ++m) _Pragma("unroll") for (int k = 0; k < 2; ++k) dst[m][k] = *(const PG8_LAS bf16x8*)(lds + PG8_SA(b, h) + aoff + m * 2048 + k * 1024); } while (0)
; #define PG8_MMA(ai, bj, At, Bt) do { __builtin_amdgcn_s_setprio(1); _Pragma("unroll") for (int m = 0; m < 4; ++m) _Pragma("unroll") for (int n = 0; n < 2; ++n) _Pragma("unroll") for (int k = 0; k < 2; ++k) \
;         acc[ai][bj][m][n] = __builtin_amdgcn_mfma_f32_16x16x32_bf16(Bt[n][k], At[m][k], acc[ai][bj][m][n], 0, 0, 0); __builtin_amdgcn_s_setprio(0); } while (0)
; #define PG8_WAIT_V(n) asm volatile("s_waitcnt vmcnt(" #n ")" ::: "memory")
; #define PG8_WAIT_L(n) asm volatile("s_waitcnt lgkmcnt(" #n ")" ::: "memory")
; #define PG8_BAR __builtin_amdgcn_s_barrier()
; #define PG8_SCHED __builtin_amdgcn_sched_barrier(0)
; template <class Epi, class Sched, bool ALIGN_EPI = false, bool SP2 = false>
; __device__ __forceinline__ void gemm_phase(PG8_LAS unsigned char* lds, const Gemm g, const Sched& S, const Epi& E) {
;     ...
;             PG8_LDA(At, 1, 1); PG8_STAGE(PG8_SB(1, 0), b3, voffB); PG8_STAGE(PG8_SB(1, 1), b3 + hstep, voffB); PG8_STAGE(PG8_SA(1, 0), a3, voffA);
;             PG8_WAIT_V(8); PG8_WAIT_L(0); PG8_BAR; PG8_MMA(1, 0, At, B0); PG8_MMA(1, 1, At, B1); PG8_BAR; PG8_SCHED;
	s_add_i32 s24, s26, s30
	v_lshl_add_u64 v[222:223], v[232:233], 0, s[64:65]
	s_mov_b32 m0, s24
	ds_read_b128 v[180:183], v247 offset:49152
	ds_read_b128 v[184:187], v247 offset:50176
	ds_read_b128 v[188:191], v247 offset:51200
	ds_read_b128 v[192:195], v247 offset:52224
	ds_read_b128 v[196:199], v247 offset:53248
	ds_read_b128 v[200:203], v247 offset:54272
	ds_read_b128 v[204:207], v247 offset:55296
	ds_read_b128 v[208:211], v247 offset:56320
	global_load_lds_dwordx4 v[222:223], off
	s_add_i32 m0, s24, 0x2000
	s_add_u32 s22, s22, 0x80080
	v_lshl_add_u64 v[222:223], v[248:249], 0, s[64:65]
	s_addc_u32 s23, s23, 0
	s_add_i32 s24, s27, s30
	global_load_lds_dwordx4 v[222:223], off
	v_lshl_add_u64 v[222:223], s[22:23], 0, v[0:1]
	s_mov_b32 m0, s24
	v_lshl_add_u64 v[220:221], v[220:221], 0, s[64:65]
	global_load_lds_dwordx4 v[222:223], off
	v_lshl_add_u64 v[222:223], s[22:23], 0, v[126:127]
	s_add_i32 m0, s24, 0x2000
	s_nop 0
	global_load_lds_dwordx4 v[222:223], off
	v_lshl_add_u64 v[222:223], v[250:251], 0, s[64:65]
	s_mov_b32 m0, s37
	s_nop 0
	global_load_lds_dwordx4 v[222:223], off
	s_mov_b32 m0, s84
	s_nop 0
	global_load_lds_dwordx4 v[220:221], off
	s_waitcnt vmcnt(8)
	s_waitcnt lgkmcnt(0)
	s_barrier
	s_setprio 1
	v_mfma_f32_16x16x32_bf16 v[62:65], v[148:151], v[180:183], v[62:65]
	v_mfma_f32_16x16x32_bf16 v[58:61], v[156:159], v[180:183], v[58:61]
	v_mfma_f32_16x16x32_bf16 v[46:49], v[148:151], v[188:191], v[46:49]
	v_mfma_f32_16x16x32_bf16 v[42:45], v[156:159], v[188:191], v[42:45]
	v_mfma_f32_16x16x32_bf16 v[30:33], v[148:151], v[196:199], v[30:33]
	v_mfma_f32_16x16x32_bf16 v[26:29], v[156:159], v[196:199], v[26:29]
	v_mfma_f32_16x16x32_bf16 v[14:17], v[148:151], v[204:207], v[14:17]
	v_mfma_f32_16x16x32_bf16 v[10:13], v[156:159], v[204:207], v[10:13]
	v_mfma_f32_16x16x32_bf16 v[62:65], v[152:155], v[184:187], v[62:65]
	v_mfma_f32_16x16x32_bf16 v[58:61], v[160:163], v[184:187], v[58:61]
	v_mfma_f32_16x16x32_bf16 v[46:49], v[152:155], v[192:195], v[46:49]
	v_mfma_f32_16x16x32_bf16 v[42:45], v[160:163], v[192:195], v[42:45]
	v_mfma_f32_16x16x32_bf16 v[30:33], v[152:155], v[200:203], v[30:33]
	v_mfma_f32_16x16x32_bf16 v[26:29], v[160:163], v[200:203], v[26:29]
	v_mfma_f32_16x16x32_bf16 v[14:17], v[152:155], v[208:211], v[14:17]
	v_mfma_f32_16x16x32_bf16 v[10:13], v[160:163], v[208:211], v[10:13]
	v_mfma_f32_16x16x32_bf16 v[54:57], v[164:167], v[180:183], v[54:57]
	v_mfma_f32_16x16x32_bf16 v[50:53], v[172:175], v[180:183], v[50:53]
	v_mfma_f32_16x16x32_bf16 v[38:41], v[164:167], v[188:191], v[38:41]
	v_mfma_f32_16x16x32_bf16 v[34:37], v[172:175], v[188:191], v[34:37]
	v_mfma_f32_16x16x32_bf16 v[22:25], v[164:167], v[196:199], v[22:25]
	v_mfma_f32_16x16x32_bf16 v[18:21], v[172:175], v[196:199], v[18:21]
	v_mfma_f32_16x16x32_bf16 v[6:9], v[164:167], v[204:207], v[6:9]
	v_mfma_f32_16x16x32_bf16 v[2:5], v[172:175], v[204:207], v[2:5]
	v_mfma_f32_16x16x32_bf16 v[54:57], v[168:171], v[184:187], v[54:57]
	v_mfma_f32_16x16x32_bf16 v[50:53], v[176:179], v[184:187], v[50:53]
	v_mfma_f32_16x16x32_bf16 v[38:41], v[168:171], v[192:195], v[38:41]
	v_mfma_f32_16x16x32_bf16 v[34:37], v[176:179], v[192:195], v[34:37]
	v_mfma_f32_16x16x32_bf16 v[22:25], v[168:171], v[200:203], v[22:25]
	v_mfma_f32_16x16x32_bf16 v[18:21], v[176:179], v[200:203], v[18:21]
	v_mfma_f32_16x16x32_bf16 v[6:9], v[168:171], v[208:211], v[6:9]
	v_mfma_f32_16x16x32_bf16 v[2:5], v[176:179], v[208:211], v[2:5]
	s_setprio 0
	s_barrier
	s_add_i32 s22, s76, 2
	s_add_u32 s20, s20, 0x100
	s_addc_u32 s21, s21, 0
	s_cmp_gt_u32 s76, 29
	s_mov_b32 s76, s22
	s_cbranch_scc1 .LBB0_742

;     __device__ __forceinline__ bool next(int i, Unit& u) const { if (i > 0 || c < first) return false; const int idx = c - first; u.pm = idx % nM; u.pn = idx / nM; return true; }
; #define PG8_STAGE(bufoff, gbase, voff) do { _Pragma("unroll") for (int _i = 0; _i < 2; ++_i) \
;         __builtin_amdgcn_global_load_lds((const unsigned*)((const char*)(gbase) + (voff)[_i]), (PG8_LAS unsigned*)(lds + (bufoff) + ldsw + _i * 8192), 16, 0, 0); } while (0)
; #define PG8_LDA(dst, b, h) do { _Pragma("unroll") for (int m = 0; m < 4; ++m) _Pragma("unroll") for (int k = 0; k < 2; ++k) dst[m][k] = *(const PG8_LAS bf16x8*)(lds + PG8_SA(b, h) + aoff + m * 2048 + k * 1024); } while (0)
; #define PG8_WAIT_V(n) asm volatile("s_waitcnt vmcnt(" #n ")" ::: "memory")
; #define PG8_WAIT_L(n) asm volatile("s_waitcnt lgkmcnt(" #n ")" ::: "memory")
; #define PG8_BAR __builtin_amdgcn_s_barrier()
; template <class Epi, class Sched, bool ALIGN_EPI = false, bool SP2 = false>
; __device__ __forceinline__ void gemm_phase(PG8_LAS unsigned char* lds, const Gemm g, const Sched& S, const Epi& E) {
;     ...
;         const bool has_next = S.next(ui + 1, nxt);
;         const char* nA = has_next ? (const char*)g.A + (size_t)nxt.pm * tstep : cA; const char* nB = has_next ? (const char*)g.Bt + (size_t)nxt.pn * tstep : cB;
;         for (int t = 0; t < nt; t += 2) {
;             if constexpr (Epi::HAS_MID) { if (t == Epi::MID0 || t == Epi::MID1) E.mid(acc, cur, wr, wc, fr, fq, t == Epi::MID0 ? 0 : 1); }
;             const bool last = (t == nt - 2);
;             const char* a1 = cA + (size_t)(t + 1) * kstep;
;             const char* a2 = last ? nA : cA + (size_t)(t + 2) * kstep; const char* b2 = last ? nB : cB + (size_t)(t + 2) * kstep;
;             const char* a3 = a2 + kstep; const char* b3 = b2 + kstep;
;             if (last && has_next) S.a_ready(nxt);
;             if constexpr (SP2) {
;             PG8_LDB(B0, 0, 0); PG8_LDB(B1, 0, 1); PG8_SCHED; PG8_LDA(At, 0, 0); PG8_STAGE(PG8_SA(1, 1), a1 + hstep, voffA);
;             PG8_WAIT_V(8); PG8_WAIT_L(0); PG8_BAR; PG8_MMA(0, 0, At, B0); PG8_MMA(0, 1, At, B1); PG8_BAR; PG8_SCHED;
;             PG8_LDA(At, 0, 1); PG8_STAGE(PG8_SB(0, 0), b2, voffB); PG8_STAGE(PG8_SB(0, 1), b2 + hstep, voffB); PG8_STAGE(PG8_SA(0, 0), a2, voffA);
;             PG8_WAIT_V(8); PG8_WAIT_L(0); PG8_BAR; PG8_MMA(1, 0, At, B0); PG8_MMA(1, 1, At, B1); PG8_BAR; PG8_SCHED;
.LBB0_808:
	s_add_u32 s28, s8, 0xfff80080
	s_addc_u32 s29, s9, -1
	s_add_i32 s48, 0, 0x10000
	s_cmp_eq_u32 s87, 28
	s_cselect_b32 s31, s23, s29
	s_cselect_b32 s30, s67, s28
	v_add_u32_e32 v160, s48, v163
	s_cselect_b32 s29, s21, s86
	s_cselect_b32 s28, s81, s83
	s_add_i32 s91, 0, 0x14000
	ds_read_b128 v[152:155], v160
	ds_read_b128 v[156:159], v160 offset:1024
	ds_read_b128 v[166:169], v160 offset:2048
	ds_read_b128 v[170:173], v160 offset:3072
	v_add_u32_e32 v160, s91, v163
	ds_read_b128 v[174:177], v160
	ds_read_b128 v[178:181], v160 offset:1024
	ds_read_b128 v[182:185], v160 offset:2048
	ds_read_b128 v[186:189], v160 offset:3072
	v_lshl_add_u64 v[160:161], s[8:9], 0, v[148:149]
	s_add_i32 m0, s13, 0xc000
	ds_read_b128 v[190:193], v165
	ds_read_b128 v[194:197], v165 offset:1024
	ds_read_b128 v[198:201], v165 offset:2048
	ds_read_b128 v[202:205], v165 offset:3072
	ds_read_b128 v[206:209], v165 offset:4096
	ds_read_b128 v[210:213], v165 offset:5120
	ds_read_b128 v[214:217], v165 offset:6144
	ds_read_b128 v[224:227], v165 offset:7168
	global_load_lds_dwordx4 v[160:161], off
	v_lshl_add_u64 v[160:161], s[8:9], 0, v[150:151]
	s_add_i32 m0, s13, 0xe000
	s_nop 0
	global_load_lds_dwordx4 v[160:161], off
	s_waitcnt vmcnt(8)
	s_waitcnt lgkmcnt(0)
	s_barrier
	s_setprio 1
	v_mfma_f32_16x16x32_bf16 v[144:147], v[152:155], v[190:193], v[144:147]
	v_mfma_f32_16x16x32_bf16 v[122:125], v[166:169], v[190:193], v[122:125]
	v_mfma_f32_16x16x32_bf16 v[110:113], v[152:155], v[198:201], v[110:113]
	v_mfma_f32_16x16x32_bf16 v[106:109], v[166:169], v[198:201], v[106:109]
	v_mfma_f32_16x16x32_bf16 v[94:97], v[152:155], v[206:209], v[94:97]
	v_mfma_f32_16x16x32_bf16 v[90:93], v[166:169], v[206:209], v[90:93]
	v_mfma_f32_16x16x32_bf16 v[78:81], v[152:155], v[214:217], v[78:81]
	v_mfma_f32_16x16x32_bf16 v[74:77], v[166:169], v[214:217], v[74:77]
	v_mfma_f32_16x16x32_bf16 v[144:147], v[156:159], v[194:197], v[144:147]
	v_mfma_f32_16x16x32_bf16 v[122:125], v[170:173], v[194:197], v[122:125]
	v_mfma_f32_16x16x32_bf16 v[110:113], v[156:159], v[202:205], v[110:113]
	v_mfma_f32_16x16x32_bf16 v[106:109], v[170:173], v[202:205], v[106:109]
	v_mfma_f32_16x16x32_bf16 v[94:97], v[156:159], v[210:213], v[94:97]
	v_mfma_f32_16x16x32_bf16 v[90:93], v[170:173], v[210:213], v[90:93]
	v_mfma_f32_16x16x32_bf16 v[78:81], v[156:159], v[224:227], v[78:81]
	v_mfma_f32_16x16x32_bf16 v[74:77], v[170:173], v[224:227], v[74:77]
	v_mfma_f32_16x16x32_bf16 v[118:121], v[174:177], v[190:193], v[118:121]
	v_mfma_f32_16x16x32_bf16 v[114:117], v[182:185], v[190:193], v[114:117]
	v_mfma_f32_16x16x32_bf16 v[102:105], v[174:177], v[198:201], v[102:105]
	v_mfma_f32_16x16x32_bf16 v[98:101], v[182:185], v[198:201], v[98:101]
	v_mfma_f32_16x16x32_bf16 v[86:89], v[174:177], v[206:209], v[86:89]
	v_mfma_f32_16x16x32_bf16 v[82:85], v[182:185], v[206:209], v[82:85]
	v_mfma_f32_16x16x32_bf16 v[70:73], v[174:177], v[214:217], v[70:73]
	v_mfma_f32_16x16x32_bf16 v[66:69], v[182:185], v[214:217], v[66:69]
	v_mfma_f32_16x16x32_bf16 v[118:121], v[178:181], v[194:197], v[118:121]
	v_mfma_f32_16x16x32_bf16 v[114:117], v[186:189], v[194:197], v[114:117]
	v_mfma_f32_16x16x32_bf16 v[102:105], v[178:181], v[202:205], v[102:105]
	v_mfma_f32_16x16x32_bf16 v[98:101], v[186:189], v[202:205], v[98:101]
	v_mfma_f32_16x16x32_bf16 v[86:89], v[178:181], v[210:213], v[86:89]
	v_mfma_f32_16x16x32_bf16 v[82:85], v[186:189], v[210:213], v[82:85]
	v_mfma_f32_16x16x32_bf16 v[70:73], v[178:181], v[224:227], v[70:73]
	v_mfma_f32_16x16x32_bf16 v[66:69], v[186:189], v[224:227], v[66:69]
	s_setprio 0
	s_barrier
	s_add_i32 s48, s48, s12
	v_lshl_add_u64 v[160:161], s[28:29], 0, v[0:1]
	s_mov_b32 m0, s48
	ds_read_b128 v[190:193], v165 offset:16384
	ds_read_b128 v[194:197], v165 offset:17408
	ds_read_b128 v[198:201], v165 offset:18432
	ds_read_b128 v[202:205], v165 offset:19456
	ds_read_b128 v[206:209], v165 offset:20480
	ds_read_b128 v[210:213], v165 offset:21504
	ds_read_b128 v[214:217], v165 offset:22528
	ds_read_b128 v[224:227], v165 offset:23552
	global_load_lds_dwordx4 v[160:161], off
	s_add_i32 m0, s48, 0x2000
	s_add_u32 vcc_lo, s28, 0x80000
	v_lshl_add_u64 v[218:219], s[28:29], 0, v[126:127]
	s_addc_u32 vcc_hi, s29, 0
	s_add_i32 s48, s91, s12
	global_load_lds_dwordx4 v[218:219], off
	v_lshl_add_u64 v[220:221], vcc, 0, v[0:1]
	s_mov_b32 m0, s48
	v_lshl_add_u64 v[222:223], s[30:31], 0, v[126:127]
	global_load_lds_dwordx4 v[220:221], off
	v_lshl_add_u64 v[220:221], vcc, 0, v[126:127]
	s_add_i32 m0, s48, 0x2000
	s_nop 0
	global_load_lds_dwordx4 v[220:221], off
	v_lshl_add_u64 v[220:221], s[30:31], 0, v[0:1]
	s_mov_b32 m0, s13
	s_nop 0
	global_load_lds_dwordx4 v[220:221], off
	s_mov_b32 m0, s34
	s_nop 0
	global_load_lds_dwordx4 v[222:223], off
	s_waitcnt vmcnt(8)
	s_waitcnt lgkmcnt(0)
	s_barrier
; #define PG8_STAGE(bufoff, gbase, voff) do { _Pragma("unroll") for (int _i = 0; _i < 2; ++_i) \
;         __builtin_amdgcn_global_load_lds((const unsigned*)((const char*)(gbase) + (voff)[_i]), (PG8_LAS unsigned*)(lds + (bufoff) + ldsw + _i * 8192), 16, 0, 0); } while (0)
; #define PG8_LDA(dst, b, h) do { _Pragma("unroll") for (int m = 0; m < 4; ++m) _Pragma("unroll") for (int k = 0; k < 2; ++k) dst[m][k] = *(const PG8_LAS bf16x8*)(lds + PG8_SA(b, h) + aoff + m * 2048 + k * 1024); } while (0)
; #define PG8_LDB(dst, b, h) do { _Pragma("unroll") for (int n = 0; n < 2; ++n) _Pragma("unroll") for (int k = 0; k < 2; ++k) dst[n][k] = *(const PG8_LAS bf16x8*)(lds + PG8_SB(b, h) + boff + n * 2048 + k * 1024); } while (0)
; #define PG8_MMA(ai, bj, At, Bt) do { __builtin_amdgcn_s_setprio(1); _Pragma("unroll") for (int m = 0; m < 4; ++m) _Pragma("unroll") for (int n = 0; n < 2; ++n) _Pragma("unroll") for (int k = 0; k < 2; ++k) \
;         acc[ai][bj][m][n] = __builtin_amdgcn_mfma_f32_16x16x32_bf16(Bt[n][k], At[m][k], acc[ai][bj][m][n], 0, 0, 0); __builtin_amdgcn_s_setprio(0); } while (0)
; #define PG8_WAIT_V(n) asm volatile("s_waitcnt vmcnt(" #n ")" ::: "memory")
; #define PG8_WAIT_L(n) asm volatile("s_waitcnt lgkmcnt(" #n ")" ::: "memory")
; #define PG8_BAR __builtin_amdgcn_s_barrier()
; #define PG8_SCHED __builtin_amdgcn_sched_barrier(0)
; template <class Epi, class Sched, bool ALIGN_EPI = false, bool SP2 = false>
; __device__ __forceinline__ void gemm_phase(PG8_LAS unsigned char* lds, const Gemm g, const Sched& S, const Epi& E) {
;     ...
;             PG8_WAIT_V(8); PG8_WAIT_L(0); PG8_BAR; PG8_MMA(1, 0, At, B0); PG8_MMA(1, 1, At, B1); PG8_BAR; PG8_SCHED;
;             PG8_LDB(B0, 1, 0); PG8_LDB(B1, 1, 1); PG8_SCHED; PG8_LDA(At, 1, 0); PG8_STAGE(PG8_SA(0, 1), a2 + hstep, voffA);
;             PG8_WAIT_V(8); PG8_WAIT_L(0); PG8_BAR; PG8_MMA(0, 0, At, B0); PG8_MMA(0, 1, At, B1); PG8_BAR; PG8_SCHED;
	s_setprio 1
	v_mfma_f32_16x16x32_bf16 v[62:65], v[152:155], v[190:193], v[62:65]
	v_mfma_f32_16x16x32_bf16 v[58:61], v[166:169], v[190:193], v[58:61]
	v_mfma_f32_16x16x32_bf16 v[46:49], v[152:155], v[198:201], v[46:49]
	v_mfma_f32_16x16x32_bf16 v[42:45], v[166:169], v[198:201], v[42:45]
	v_mfma_f32_16x16x32_bf16 v[30:33], v[152:155], v[206:209], v[30:33]
	v_mfma_f32_16x16x32_bf16 v[26:29], v[166:169], v[206:209], v[26:29]
	v_mfma_f32_16x16x32_bf16 v[14:17], v[152:155], v[214:217], v[14:17]
	v_mfma_f32_16x16x32_bf16 v[10:13], v[166:169], v[214:217], v[10:13]
	v_mfma_f32_16x16x32_bf16 v[62:65], v[156:159], v[194:197], v[62:65]
	v_mfma_f32_16x16x32_bf16 v[58:61], v[170:173], v[194:197], v[58:61]
	v_mfma_f32_16x16x32_bf16 v[46:49], v[156:159], v[202:205], v[46:49]
	v_mfma_f32_16x16x32_bf16 v[42:45], v[170:173], v[202:205], v[42:45]
	v_mfma_f32_16x16x32_bf16 v[30:33], v[156:159], v[210:213], v[30:33]
	v_mfma_f32_16x16x32_bf16 v[26:29], v[170:173], v[210:213], v[26:29]
	v_mfma_f32_16x16x32_bf16 v[14:17], v[156:159], v[224:227], v[14:17]
	v_mfma_f32_16x16x32_bf16 v[10:13], v[170:173], v[224:227], v[10:13]
	v_mfma_f32_16x16x32_bf16 v[54:57], v[174:177], v[190:193], v[54:57]
	v_mfma_f32_16x16x32_bf16 v[50:53], v[182:185], v[190:193], v[50:53]
	v_mfma_f32_16x16x32_bf16 v[38:41], v[174:177], v[198:201], v[38:41]
	v_mfma_f32_16x16x32_bf16 v[34:37], v[182:185], v[198:201], v[34:37]
	v_mfma_f32_16x16x32_bf16 v[22:25], v[174:177], v[206:209], v[22:25]
	v_mfma_f32_16x16x32_bf16 v[18:21], v[182:185], v[206:209], v[18:21]
	v_mfma_f32_16x16x32_bf16 v[6:9], v[174:177], v[214:217], v[6:9]
	v_mfma_f32_16x16x32_bf16 v[2:5], v[182:185], v[214:217], v[2:5]
	v_mfma_f32_16x16x32_bf16 v[54:57], v[178:181], v[194:197], v[54:57]
	v_mfma_f32_16x16x32_bf16 v[50:53], v[186:189], v[194:197], v[50:53]
	v_mfma_f32_16x16x32_bf16 v[38:41], v[178:181], v[202:205], v[38:41]
	v_mfma_f32_16x16x32_bf16 v[34:37], v[186:189], v[202:205], v[34:37]
	v_mfma_f32_16x16x32_bf16 v[22:25], v[178:181], v[210:213], v[22:25]
	v_mfma_f32_16x16x32_bf16 v[18:21], v[186:189], v[210:213], v[18:21]
	v_mfma_f32_16x16x32_bf16 v[6:9], v[178:181], v[224:227], v[6:9]
	v_mfma_f32_16x16x32_bf16 v[2:5], v[186:189], v[224:227], v[2:5]
	s_setprio 0
	s_barrier
	s_add_i32 s48, 0, 0x18000
	s_add_i32 s91, 0, 0x1c000
	v_add_u32_e32 v170, s48, v163
	v_add_u32_e32 v186, s91, v163
	ds_read_b128 v[152:155], v170
	ds_read_b128 v[156:159], v170 offset:1024
	ds_read_b128 v[166:169], v170 offset:2048
	ds_read_b128 v[170:173], v170 offset:3072
	ds_read_b128 v[174:177], v186
	ds_read_b128 v[178:181], v186 offset:1024
	ds_read_b128 v[182:185], v186 offset:2048
	ds_read_b128 v[186:189], v186 offset:3072
	s_add_u32 s30, s30, 0x80000
	s_addc_u32 s31, s31, 0
	s_mov_b32 m0, s35
	v_lshl_add_u64 v[228:229], s[30:31], 0, v[0:1]
	ds_read_b128 v[190:193], v165 offset:32768
	ds_read_b128 v[194:197], v165 offset:33792
	ds_read_b128 v[198:201], v165 offset:34816
	ds_read_b128 v[202:205], v165 offset:35840
	ds_read_b128 v[206:209], v165 offset:36864
	ds_read_b128 v[210:213], v165 offset:37888
	ds_read_b128 v[214:217], v165 offset:38912
	ds_read_b128 v[224:227], v165 offset:39936
	global_load_lds_dwordx4 v[228:229], off
	v_lshl_add_u64 v[228:229], s[30:31], 0, v[126:127]
	s_mov_b32 m0, s42
	s_nop 0
	global_load_lds_dwordx4 v[228:229], off
	s_waitcnt vmcnt(8)
	s_waitcnt lgkmcnt(0)
	s_barrier
	s_setprio 1
	v_mfma_f32_16x16x32_bf16 v[144:147], v[152:155], v[190:193], v[144:147]
	v_mfma_f32_16x16x32_bf16 v[122:125], v[166:169], v[190:193], v[122:125]
	v_mfma_f32_16x16x32_bf16 v[110:113], v[152:155], v[198:201], v[110:113]
	v_mfma_f32_16x16x32_bf16 v[106:109], v[166:169], v[198:201], v[106:109]
	v_mfma_f32_16x16x32_bf16 v[94:97], v[152:155], v[206:209], v[94:97]
	v_mfma_f32_16x16x32_bf16 v[90:93], v[166:169], v[206:209], v[90:93]
	v_mfma_f32_16x16x32_bf16 v[78:81], v[152:155], v[214:217], v[78:81]
	v_mfma_f32_16x16x32_bf16 v[74:77], v[166:169], v[214:217], v[74:77]
	v_mfma_f32_16x16x32_bf16 v[144:147], v[156:159], v[194:197], v[144:147]
	v_mfma_f32_16x16x32_bf16 v[122:125], v[170:173], v[194:197], v[122:125]
	v_mfma_f32_16x16x32_bf16 v[110:113], v[156:159], v[202:205], v[110:113]
	v_mfma_f32_16x16x32_bf16 v[106:109], v[170:173], v[202:205], v[106:109]
	v_mfma_f32_16x16x32_bf16 v[94:97], v[156:159], v[210:213], v[94:97]
	v_mfma_f32_16x16x32_bf16 v[90:93], v[170:173], v[210:213], v[90:93]
	v_mfma_f32_16x16x32_bf16 v[78:81], v[156:159], v[224:227], v[78:81]
	v_mfma_f32_16x16x32_bf16 v[74:77], v[170:173], v[224:227], v[74:77]
	v_mfma_f32_16x16x32_bf16 v[118:121], v[174:177], v[190:193], v[118:121]
	v_mfma_f32_16x16x32_bf16 v[114:117], v[182:185], v[190:193], v[114:117]
	v_mfma_f32_16x16x32_bf16 v[102:105], v[174:177], v[198:201], v[102:105]
	v_mfma_f32_16x16x32_bf16 v[98:101], v[182:185], v[198:201], v[98:101]
	v_mfma_f32_16x16x32_bf16 v[86:89], v[174:177], v[206:209], v[86:89]
	v_mfma_f32_16x16x32_bf16 v[82:85], v[182:185], v[206:209], v[82:85]
	v_mfma_f32_16x16x32_bf16 v[70:73], v[174:177], v[214:217], v[70:73]
	v_mfma_f32_16x16x32_bf16 v[66:69], v[182:185], v[214:217], v[66:69]
	v_mfma_f32_16x16x32_bf16 v[118:121], v[178:181], v[194:197], v[118:121]
	v_mfma_f32_16x16x32_bf16 v[114:117], v[186:189], v[194:197], v[114:117]
	v_mfma_f32_16x16x32_bf16 v[102:105], v[178:181], v[202:205], v[102:105]
	v_mfma_f32_16x16x32_bf16 v[98:101], v[186:189], v[202:205], v[98:101]
	v_mfma_f32_16x16x32_bf16 v[86:89], v[178:181], v[210:213], v[86:89]
	v_mfma_f32_16x16x32_bf16 v[82:85], v[186:189], v[210:213], v[82:85]
	v_mfma_f32_16x16x32_bf16 v[70:73], v[178:181], v[224:227], v[70:73]
	v_mfma_f32_16x16x32_bf16 v[66:69], v[186:189], v[224:227], v[66:69]
	s_setprio 0
	s_barrier
; #define PG8_STAGE(bufoff, gbase, voff) do { _Pragma("unroll") for (int _i = 0; _i < 2; ++_i) \
;         __builtin_amdgcn_global_load_lds((const unsigned*)((const char*)(gbase) + (voff)[_i]), (PG8_LAS unsigned*)(lds + (bufoff) + ldsw + _i * 8192), 16, 0, 0); } while (0)
; #define PG8_LDA(dst, b, h) do { _Pragma("unroll") for (int m = 0; m < 4; ++m) _Pragma("unroll") for (int k = 0; k < 2; ++k) dst[m][k] = *(const PG8_LAS bf16x8*)(lds + PG8_SA(b, h) + aoff + m * 2048 + k * 1024); } while (0)
; #define PG8_MMA(ai, bj, At, Bt) do { __builtin_amdgcn_s_setprio(1); _Pragma("unroll") for (int m = 0; m < 4; ++m) _Pragma("unroll") for (int n = 0; n < 2; ++n) _Pragma("unroll") for (int k = 0; k < 2; ++k) \
;         acc[ai][bj][m][n] = __builtin_amdgcn_mfma_f32_16x16x32_bf16(Bt[n][k], At[m][k], acc[ai][bj][m][n], 0, 0, 0); __builtin_amdgcn_s_setprio(0); } while (0)
; #define PG8_WAIT_V(n) asm volatile("s_waitcnt vmcnt(" #n ")" ::: "memory")
; #define PG8_WAIT_L(n) asm volatile("s_waitcnt lgkmcnt(" #n ")" ::: "memory")
; #define PG8_BAR __builtin_amdgcn_s_barrier()
; #define PG8_SCHED __builtin_amdgcn_sched_barrier(0)
; template <class Epi, class Sched, bool ALIGN_EPI = false, bool SP2 = false>
; __device__ __forceinline__ void gemm_phase(PG8_LAS unsigned char* lds, const Gemm g, const Sched& S, const Epi& E) {
;     ...
;         for (int t = 0; t < nt; t += 2) {
;     ...
;             PG8_LDA(At, 1, 1); PG8_STAGE(PG8_SB(1, 0), b3, voffB); PG8_STAGE(PG8_SB(1, 1), b3 + hstep, voffB); PG8_STAGE(PG8_SA(1, 0), a3, voffA);
;             PG8_WAIT_V(8); PG8_WAIT_L(0); PG8_BAR; PG8_MMA(1, 0, At, B0); PG8_MMA(1, 1, At, B1); PG8_BAR; PG8_SCHED;
	s_add_i32 s30, s48, s12
	v_lshl_add_u64 v[160:161], v[160:161], 0, s[64:65]
	s_mov_b32 m0, s30
	ds_read_b128 v[190:193], v165 offset:49152
	ds_read_b128 v[194:197], v165 offset:50176
	ds_read_b128 v[198:201], v165 offset:51200
	ds_read_b128 v[202:205], v165 offset:52224
	ds_read_b128 v[206:209], v165 offset:53248
	ds_read_b128 v[210:213], v165 offset:54272
	ds_read_b128 v[214:217], v165 offset:55296
	ds_read_b128 v[224:227], v165 offset:56320
	global_load_lds_dwordx4 v[160:161], off
	s_add_i32 m0, s30, 0x2000
	s_add_u32 s28, s28, 0x80080
	v_lshl_add_u64 v[160:161], v[218:219], 0, s[64:65]
	s_addc_u32 s29, s29, 0
	s_add_i32 s30, s91, s12
	global_load_lds_dwordx4 v[160:161], off
	v_lshl_add_u64 v[160:161], s[28:29], 0, v[0:1]
	s_mov_b32 m0, s30
	s_nop 0
	global_load_lds_dwordx4 v[160:161], off
	v_lshl_add_u64 v[160:161], s[28:29], 0, v[126:127]
	s_add_i32 m0, s30, 0x2000
	s_nop 0
	global_load_lds_dwordx4 v[160:161], off
	v_lshl_add_u64 v[160:161], v[220:221], 0, s[64:65]
	s_mov_b32 m0, s43
	s_nop 0
	global_load_lds_dwordx4 v[160:161], off
	v_lshl_add_u64 v[160:161], v[222:223], 0, s[64:65]
	s_mov_b32 m0, s76
	s_nop 0
	global_load_lds_dwordx4 v[160:161], off
	s_waitcnt vmcnt(8)
	s_waitcnt lgkmcnt(0)
	s_barrier
	s_setprio 1
	v_mfma_f32_16x16x32_bf16 v[62:65], v[152:155], v[190:193], v[62:65]
	v_mfma_f32_16x16x32_bf16 v[58:61], v[166:169], v[190:193], v[58:61]
	v_mfma_f32_16x16x32_bf16 v[46:49], v[152:155], v[198:201], v[46:49]
	v_mfma_f32_16x16x32_bf16 v[42:45], v[166:169], v[198:201], v[42:45]
	v_mfma_f32_16x16x32_bf16 v[30:33], v[152:155], v[206:209], v[30:33]
	v_mfma_f32_16x16x32_bf16 v[26:29], v[166:169], v[206:209], v[26:29]
	v_mfma_f32_16x16x32_bf16 v[14:17], v[152:155], v[214:217], v[14:17]
	v_mfma_f32_16x16x32_bf16 v[10:13], v[166:169], v[214:217], v[10:13]
	v_mfma_f32_16x16x32_bf16 v[62:65], v[156:159], v[194:197], v[62:65]
	v_mfma_f32_16x16x32_bf16 v[58:61], v[170:173], v[194:197], v[58:61]
	v_mfma_f32_16x16x32_bf16 v[46:49], v[156:159], v[202:205], v[46:49]
	v_mfma_f32_16x16x32_bf16 v[42:45], v[170:173], v[202:205], v[42:45]
	v_mfma_f32_16x16x32_bf16 v[30:33], v[156:159], v[210:213], v[30:33]
	v_mfma_f32_16x16x32_bf16 v[26:29], v[170:173], v[210:213], v[26:29]
	v_mfma_f32_16x16x32_bf16 v[14:17], v[156:159], v[224:227], v[14:17]
	v_mfma_f32_16x16x32_bf16 v[10:13], v[170:173], v[224:227], v[10:13]
	v_mfma_f32_16x16x32_bf16 v[54:57], v[174:177], v[190:193], v[54:57]
	v_mfma_f32_16x16x32_bf16 v[50:53], v[182:185], v[190:193], v[50:53]
	v_mfma_f32_16x16x32_bf16 v[38:41], v[174:177], v[198:201], v[38:41]
	v_mfma_f32_16x16x32_bf16 v[34:37], v[182:185], v[198:201], v[34:37]
	v_mfma_f32_16x16x32_bf16 v[22:25], v[174:177], v[206:209], v[22:25]
	v_mfma_f32_16x16x32_bf16 v[18:21], v[182:185], v[206:209], v[18:21]
	v_mfma_f32_16x16x32_bf16 v[6:9], v[174:177], v[214:217], v[6:9]
	v_mfma_f32_16x16x32_bf16 v[2:5], v[182:185], v[214:217], v[2:5]
	v_mfma_f32_16x16x32_bf16 v[54:57], v[178:181], v[194:197], v[54:57]
	v_mfma_f32_16x16x32_bf16 v[50:53], v[186:189], v[194:197], v[50:53]
	v_mfma_f32_16x16x32_bf16 v[38:41], v[178:181], v[202:205], v[38:41]
	v_mfma_f32_16x16x32_bf16 v[34:37], v[186:189], v[202:205], v[34:37]
	v_mfma_f32_16x16x32_bf16 v[22:25], v[178:181], v[210:213], v[22:25]
	v_mfma_f32_16x16x32_bf16 v[18:21], v[186:189], v[210:213], v[18:21]
	v_mfma_f32_16x16x32_bf16 v[6:9], v[178:181], v[224:227], v[6:9]
	v_mfma_f32_16x16x32_bf16 v[2:5], v[186:189], v[224:227], v[2:5]
	s_setprio 0
	s_barrier
	s_add_i32 s87, s87, 2
	s_add_u32 s8, s8, 0x100
	s_addc_u32 s9, s9, 0
	s_add_u32 s83, s83, 0x100
	s_addc_u32 s86, s86, 0
	s_cmp_gt_u32 s87, 29
	s_cbranch_scc0 .LBB0_808
	s_and_b64 vcc, exec, s[18:19]
	s_cbranch_vccz .LBB0_811
	s_barrier

;     __device__ __forceinline__ bool next(int i, Unit& u) const { if (i > 0 || c < first) return false; const int idx = c - first; u.pm = idx % nM; u.pn = idx / nM; return true; }
; #define PG8_STAGE(bufoff, gbase, voff) do { _Pragma("unroll") for (int _i = 0; _i < 2; ++_i) \
;         __builtin_amdgcn_global_load_lds((const unsigned*)((const char*)(gbase) + (voff)[_i]), (PG8_LAS unsigned*)(lds + (bufoff) + ldsw + _i * 8192), 16, 0, 0); } while (0)
; #define PG8_LDA(dst, b, h) do { _Pragma("unroll") for (int m = 0; m < 4; ++m) _Pragma("unroll") for (int k = 0; k < 2; ++k) dst[m][k] = *(const PG8_LAS bf16x8*)(lds + PG8_SA(b, h) + aoff + m * 2048 + k * 1024); } while (0)
; #define PG8_WAIT_V(n) asm volatile("s_waitcnt vmcnt(" #n ")" ::: "memory")
; #define PG8_WAIT_L(n) asm volatile("s_waitcnt lgkmcnt(" #n ")" ::: "memory")
; #define PG8_BAR __builtin_amdgcn_s_barrier()
; template <class Epi, class Sched, bool ALIGN_EPI = false, bool SP2 = false>
; __device__ __forceinline__ void gemm_phase(PG8_LAS unsigned char* lds, const Gemm g, const Sched& S, const Epi& E) {
;     ...
;         const bool has_next = S.next(ui + 1, nxt);
;         const char* nA = has_next ? (const char*)g.A + (size_t)nxt.pm * tstep : cA; const char* nB = has_next ? (const char*)g.Bt + (size_t)nxt.pn * tstep : cB;
;         for (int t = 0; t < nt; t += 2) {
;             if constexpr (Epi::HAS_MID) { if (t == Epi::MID0 || t == Epi::MID1) E.mid(acc, cur, wr, wc, fr, fq, t == Epi::MID0 ? 0 : 1); }
;             const bool last = (t == nt - 2);
;             const char* a1 = cA + (size_t)(t + 1) * kstep;
;             const char* a2 = last ? nA : cA + (size_t)(t + 2) * kstep; const char* b2 = last ? nB : cB + (size_t)(t + 2) * kstep;
;             const char* a3 = a2 + kstep; const char* b3 = b2 + kstep;
;             if (last && has_next) S.a_ready(nxt);
;             if constexpr (SP2) {
;             PG8_LDB(B0, 0, 0); PG8_LDB(B1, 0, 1); PG8_SCHED; PG8_LDA(At, 0, 0); PG8_STAGE(PG8_SA(1, 1), a1 + hstep, voffA);
;             PG8_WAIT_V(8); PG8_WAIT_L(0); PG8_BAR; PG8_MMA(0, 0, At, B0); PG8_MMA(0, 1, At, B1); PG8_BAR; PG8_SCHED;
;             PG8_LDA(At, 0, 1); PG8_STAGE(PG8_SB(0, 0), b2, voffB); PG8_STAGE(PG8_SB(0, 1), b2 + hstep, voffB); PG8_STAGE(PG8_SA(0, 0), a2, voffA);
;             PG8_WAIT_V(8); PG8_WAIT_L(0); PG8_BAR; PG8_MMA(1, 0, At, B0); PG8_MMA(1, 1, At, B1); PG8_BAR; PG8_SCHED;
.LBB0_910:
	s_add_u32 s28, s0, 0xfff80080
	s_addc_u32 s29, s1, -1
	s_add_i32 s48, 0, 0x10000
	s_cmp_eq_u32 s81, 28
	s_cselect_b32 s31, s21, s29
	s_cselect_b32 s30, s35, s28
	s_cselect_b32 s29, s23, s67
	s_cselect_b32 s28, s40, s41
	s_add_i32 s91, 0, 0x14000
	v_add_u32_e32 v164, s48, v179
	v_add_u32_e32 v176, s91, v179
	ds_read_b128 v[152:155], v164
	ds_read_b128 v[156:159], v164 offset:1024
	ds_read_b128 v[160:163], v164 offset:2048
	ds_read_b128 v[164:167], v164 offset:3072
	ds_read_b128 v[168:171], v176
	ds_read_b128 v[172:175], v176 offset:1024
	ds_read_b128 v[182:185], v176 offset:2048
	ds_read_b128 v[186:189], v176 offset:3072
	v_lshl_add_u64 v[176:177], s[0:1], 0, v[148:149]
	s_add_i32 m0, s43, 0xc000
	ds_read_b128 v[190:193], v181
	ds_read_b128 v[194:197], v181 offset:1024
	ds_read_b128 v[198:201], v181 offset:2048
	ds_read_b128 v[202:205], v181 offset:3072
	ds_read_b128 v[206:209], v181 offset:4096
	ds_read_b128 v[210:213], v181 offset:5120
	ds_read_b128 v[214:217], v181 offset:6144
	ds_read_b128 v[224:227], v181 offset:7168
	global_load_lds_dwordx4 v[176:177], off
	v_lshl_add_u64 v[176:177], s[0:1], 0, v[150:151]
	s_add_i32 m0, s43, 0xe000
	s_nop 0
	global_load_lds_dwordx4 v[176:177], off
	s_waitcnt vmcnt(8)
	s_waitcnt lgkmcnt(0)
	s_barrier
	s_setprio 1
	v_mfma_f32_16x16x32_bf16 v[74:77], v[152:155], v[190:193], v[74:77]
	v_mfma_f32_16x16x32_bf16 v[78:81], v[160:163], v[190:193], v[78:81]
	v_mfma_f32_16x16x32_bf16 v[102:105], v[152:155], v[198:201], v[102:105]
	v_mfma_f32_16x16x32_bf16 v[106:109], v[160:163], v[198:201], v[106:109]
	v_mfma_f32_16x16x32_bf16 v[122:125], v[152:155], v[206:209], v[122:125]
	v_mfma_f32_16x16x32_bf16 v[144:147], v[160:163], v[206:209], v[144:147]
	v_mfma_f32_16x16x32_bf16 v[90:93], v[152:155], v[214:217], v[90:93]
	v_mfma_f32_16x16x32_bf16 v[86:89], v[160:163], v[214:217], v[86:89]
	v_mfma_f32_16x16x32_bf16 v[74:77], v[156:159], v[194:197], v[74:77]
	v_mfma_f32_16x16x32_bf16 v[78:81], v[164:167], v[194:197], v[78:81]
	v_mfma_f32_16x16x32_bf16 v[102:105], v[156:159], v[202:205], v[102:105]
	v_mfma_f32_16x16x32_bf16 v[106:109], v[164:167], v[202:205], v[106:109]
	v_mfma_f32_16x16x32_bf16 v[122:125], v[156:159], v[210:213], v[122:125]
	v_mfma_f32_16x16x32_bf16 v[144:147], v[164:167], v[210:213], v[144:147]
	v_mfma_f32_16x16x32_bf16 v[90:93], v[156:159], v[224:227], v[90:93]
	v_mfma_f32_16x16x32_bf16 v[86:89], v[164:167], v[224:227], v[86:89]
	v_mfma_f32_16x16x32_bf16 v[82:85], v[168:171], v[190:193], v[82:85]
	v_mfma_f32_16x16x32_bf16 v[94:97], v[182:185], v[190:193], v[94:97]
	v_mfma_f32_16x16x32_bf16 v[110:113], v[168:171], v[198:201], v[110:113]
	v_mfma_f32_16x16x32_bf16 v[118:121], v[182:185], v[198:201], v[118:121]
	v_mfma_f32_16x16x32_bf16 v[114:117], v[168:171], v[206:209], v[114:117]
	v_mfma_f32_16x16x32_bf16 v[98:101], v[182:185], v[206:209], v[98:101]
	v_mfma_f32_16x16x32_bf16 v[70:73], v[168:171], v[214:217], v[70:73]
	v_mfma_f32_16x16x32_bf16 v[66:69], v[182:185], v[214:217], v[66:69]
	v_mfma_f32_16x16x32_bf16 v[82:85], v[172:175], v[194:197], v[82:85]
	v_mfma_f32_16x16x32_bf16 v[94:97], v[186:189], v[194:197], v[94:97]
	v_mfma_f32_16x16x32_bf16 v[110:113], v[172:175], v[202:205], v[110:113]
	v_mfma_f32_16x16x32_bf16 v[118:121], v[186:189], v[202:205], v[118:121]
	v_mfma_f32_16x16x32_bf16 v[114:117], v[172:175], v[210:213], v[114:117]
	v_mfma_f32_16x16x32_bf16 v[98:101], v[186:189], v[210:213], v[98:101]
	v_mfma_f32_16x16x32_bf16 v[70:73], v[172:175], v[224:227], v[70:73]
	v_mfma_f32_16x16x32_bf16 v[66:69], v[186:189], v[224:227], v[66:69]
	s_setprio 0
	s_barrier
	s_add_i32 s48, s48, s42
	v_lshl_add_u64 v[176:177], s[28:29], 0, v[0:1]
	s_mov_b32 m0, s48
	ds_read_b128 v[190:193], v181 offset:16384
	ds_read_b128 v[194:197], v181 offset:17408
	ds_read_b128 v[198:201], v181 offset:18432
	ds_read_b128 v[202:205], v181 offset:19456
	ds_read_b128 v[206:209], v181 offset:20480
	ds_read_b128 v[210:213], v181 offset:21504
	ds_read_b128 v[214:217], v181 offset:22528
	ds_read_b128 v[224:227], v181 offset:23552
	global_load_lds_dwordx4 v[176:177], off
	s_add_i32 m0, s48, 0x2000
	s_add_u32 vcc_lo, s28, 0x80000
	v_lshl_add_u64 v[218:219], s[28:29], 0, v[126:127]
	s_addc_u32 vcc_hi, s29, 0
	s_add_i32 s48, s91, s42
	global_load_lds_dwordx4 v[218:219], off
	v_lshl_add_u64 v[220:221], vcc, 0, v[0:1]
	s_mov_b32 m0, s48
	v_lshl_add_u64 v[222:223], s[30:31], 0, v[126:127]
	global_load_lds_dwordx4 v[220:221], off
	v_lshl_add_u64 v[220:221], vcc, 0, v[126:127]
	s_add_i32 m0, s48, 0x2000
	s_nop 0
	global_load_lds_dwordx4 v[220:221], off
	v_lshl_add_u64 v[220:221], s[30:31], 0, v[0:1]
	s_mov_b32 m0, s43
	s_nop 0
	global_load_lds_dwordx4 v[220:221], off
	s_mov_b32 m0, s76
	s_nop 0
	global_load_lds_dwordx4 v[222:223], off
	s_waitcnt vmcnt(8)
	s_waitcnt lgkmcnt(0)
	s_barrier
; #define PG8_STAGE(bufoff, gbase, voff) do { _Pragma("unroll") for (int _i = 0; _i < 2; ++_i) \
;         __builtin_amdgcn_global_load_lds((const unsigned*)((const char*)(gbase) + (voff)[_i]), (PG8_LAS unsigned*)(lds + (bufoff) + ldsw + _i * 8192), 16, 0, 0); } while (0)
; #define PG8_LDA(dst, b, h) do { _Pragma("unroll") for (int m = 0; m < 4; ++m) _Pragma("unroll") for (int k = 0; k < 2; ++k) dst[m][k] = *(const PG8_LAS bf16x8*)(lds + PG8_SA(b, h) + aoff + m * 2048 + k * 1024); } while (0)
; #define PG8_LDB(dst, b, h) do { _Pragma("unroll") for (int n = 0; n < 2; ++n) _Pragma("unroll") for (int k = 0; k < 2; ++k) dst[n][k] = *(const PG8_LAS bf16x8*)(lds + PG8_SB(b, h) + boff + n * 2048 + k * 1024); } while (0)
; #define PG8_MMA(ai, bj, At, Bt) do { __builtin_amdgcn_s_setprio(1); _Pragma("unroll") for (int m = 0; m < 4; ++m) _Pragma("unroll") for (int n = 0; n < 2; ++n) _Pragma("unroll") for (int k = 0; k < 2; ++k) \
;         acc[ai][bj][m][n] = __builtin_amdgcn_mfma_f32_16x16x32_bf16(Bt[n][k], At[m][k], acc[ai][bj][m][n], 0, 0, 0); __builtin_amdgcn_s_setprio(0); } while (0)
; #define PG8_WAIT_V(n) asm volatile("s_waitcnt vmcnt(" #n ")" ::: "memory")
; #define PG8_WAIT_L(n) asm volatile("s_waitcnt lgkmcnt(" #n ")" ::: "memory")
; #define PG8_BAR __builtin_amdgcn_s_barrier()
; #define PG8_SCHED __builtin_amdgcn_sched_barrier(0)
; template <class Epi, class Sched, bool ALIGN_EPI = false, bool SP2 = false>
; __device__ __forceinline__ void gemm_phase(PG8_LAS unsigned char* lds, const Gemm g, const Sched& S, const Epi& E) {
;     ...
;             PG8_WAIT_V(8); PG8_WAIT_L(0); PG8_BAR; PG8_MMA(1, 0, At, B0); PG8_MMA(1, 1, At, B1); PG8_BAR; PG8_SCHED;
;             PG8_LDB(B0, 1, 0); PG8_LDB(B1, 1, 1); PG8_SCHED; PG8_LDA(At, 1, 0); PG8_STAGE(PG8_SA(0, 1), a2 + hstep, voffA);
;             PG8_WAIT_V(8); PG8_WAIT_L(0); PG8_BAR; PG8_MMA(0, 0, At, B0); PG8_MMA(0, 1, At, B1); PG8_BAR; PG8_SCHED;
	s_setprio 1
	v_mfma_f32_16x16x32_bf16 v[62:65], v[152:155], v[190:193], v[62:65]
	v_mfma_f32_16x16x32_bf16 v[58:61], v[160:163], v[190:193], v[58:61]
	v_mfma_f32_16x16x32_bf16 v[46:49], v[152:155], v[198:201], v[46:49]
	v_mfma_f32_16x16x32_bf16 v[42:45], v[160:163], v[198:201], v[42:45]
	v_mfma_f32_16x16x32_bf16 v[30:33], v[152:155], v[206:209], v[30:33]
	v_mfma_f32_16x16x32_bf16 v[26:29], v[160:163], v[206:209], v[26:29]
	v_mfma_f32_16x16x32_bf16 v[14:17], v[152:155], v[214:217], v[14:17]
	v_mfma_f32_16x16x32_bf16 v[10:13], v[160:163], v[214:217], v[10:13]
	v_mfma_f32_16x16x32_bf16 v[62:65], v[156:159], v[194:197], v[62:65]
	v_mfma_f32_16x16x32_bf16 v[58:61], v[164:167], v[194:197], v[58:61]
	v_mfma_f32_16x16x32_bf16 v[46:49], v[156:159], v[202:205], v[46:49]
	v_mfma_f32_16x16x32_bf16 v[42:45], v[164:167], v[202:205], v[42:45]
	v_mfma_f32_16x16x32_bf16 v[30:33], v[156:159], v[210:213], v[30:33]
	v_mfma_f32_16x16x32_bf16 v[26:29], v[164:167], v[210:213], v[26:29]
	v_mfma_f32_16x16x32_bf16 v[14:17], v[156:159], v[224:227], v[14:17]
	v_mfma_f32_16x16x32_bf16 v[10:13], v[164:167], v[224:227], v[10:13]
	v_mfma_f32_16x16x32_bf16 v[54:57], v[168:171], v[190:193], v[54:57]
	v_mfma_f32_16x16x32_bf16 v[50:53], v[182:185], v[190:193], v[50:53]
	v_mfma_f32_16x16x32_bf16 v[38:41], v[168:171], v[198:201], v[38:41]
	v_mfma_f32_16x16x32_bf16 v[34:37], v[182:185], v[198:201], v[34:37]
	v_mfma_f32_16x16x32_bf16 v[22:25], v[168:171], v[206:209], v[22:25]
	v_mfma_f32_16x16x32_bf16 v[18:21], v[182:185], v[206:209], v[18:21]
	v_mfma_f32_16x16x32_bf16 v[6:9], v[168:171], v[214:217], v[6:9]
	v_mfma_f32_16x16x32_bf16 v[2:5], v[182:185], v[214:217], v[2:5]
	v_mfma_f32_16x16x32_bf16 v[54:57], v[172:175], v[194:197], v[54:57]
	v_mfma_f32_16x16x32_bf16 v[50:53], v[186:189], v[194:197], v[50:53]
	v_mfma_f32_16x16x32_bf16 v[38:41], v[172:175], v[202:205], v[38:41]
	v_mfma_f32_16x16x32_bf16 v[34:37], v[186:189], v[202:205], v[34:37]
	v_mfma_f32_16x16x32_bf16 v[22:25], v[172:175], v[210:213], v[22:25]
	v_mfma_f32_16x16x32_bf16 v[18:21], v[186:189], v[210:213], v[18:21]
	v_mfma_f32_16x16x32_bf16 v[6:9], v[172:175], v[224:227], v[6:9]
	v_mfma_f32_16x16x32_bf16 v[2:5], v[186:189], v[224:227], v[2:5]
	s_setprio 0
	s_barrier
	s_add_i32 s48, 0, 0x18000
	s_add_i32 s91, 0, 0x1c000
	v_add_u32_e32 v164, s48, v179
	v_add_u32_e32 v186, s91, v179
	ds_read_b128 v[152:155], v164
	ds_read_b128 v[156:159], v164 offset:1024
	ds_read_b128 v[160:163], v164 offset:2048
	ds_read_b128 v[164:167], v164 offset:3072
	ds_read_b128 v[168:171], v186
	ds_read_b128 v[172:175], v186 offset:1024
	ds_read_b128 v[182:185], v186 offset:2048
	ds_read_b128 v[186:189], v186 offset:3072
	s_add_u32 s30, s30, 0x80000
	s_addc_u32 s31, s31, 0
	s_mov_b32 m0, s82
	v_lshl_add_u64 v[228:229], s[30:31], 0, v[0:1]
	ds_read_b128 v[190:193], v181 offset:32768
	ds_read_b128 v[194:197], v181 offset:33792
	ds_read_b128 v[198:201], v181 offset:34816
	ds_read_b128 v[202:205], v181 offset:35840
	ds_read_b128 v[206:209], v181 offset:36864
	ds_read_b128 v[210:213], v181 offset:37888
	ds_read_b128 v[214:217], v181 offset:38912
	ds_read_b128 v[224:227], v181 offset:39936
	global_load_lds_dwordx4 v[228:229], off
	v_lshl_add_u64 v[228:229], s[30:31], 0, v[126:127]
	s_mov_b32 m0, s83
	s_nop 0
	global_load_lds_dwordx4 v[228:229], off
	s_waitcnt vmcnt(8)
	s_waitcnt lgkmcnt(0)
	s_barrier
	s_setprio 1
	v_mfma_f32_16x16x32_bf16 v[74:77], v[152:155], v[190:193], v[74:77]
	v_mfma_f32_16x16x32_bf16 v[78:81], v[160:163], v[190:193], v[78:81]
	v_mfma_f32_16x16x32_bf16 v[102:105], v[152:155], v[198:201], v[102:105]
	v_mfma_f32_16x16x32_bf16 v[106:109], v[160:163], v[198:201], v[106:109]
	v_mfma_f32_16x16x32_bf16 v[122:125], v[152:155], v[206:209], v[122:125]
	v_mfma_f32_16x16x32_bf16 v[144:147], v[160:163], v[206:209], v[144:147]
	v_mfma_f32_16x16x32_bf16 v[90:93], v[152:155], v[214:217], v[90:93]
	v_mfma_f32_16x16x32_bf16 v[86:89], v[160:163], v[214:217], v[86:89]
	v_mfma_f32_16x16x32_bf16 v[74:77], v[156:159], v[194:197], v[74:77]
	v_mfma_f32_16x16x32_bf16 v[78:81], v[164:167], v[194:197], v[78:81]
	v_mfma_f32_16x16x32_bf16 v[102:105], v[156:159], v[202:205], v[102:105]
	v_mfma_f32_16x16x32_bf16 v[106:109], v[164:167], v[202:205], v[106:109]
	v_mfma_f32_16x16x32_bf16 v[122:125], v[156:159], v[210:213], v[122:125]
	v_mfma_f32_16x16x32_bf16 v[144:147], v[164:167], v[210:213], v[144:147]
	v_mfma_f32_16x16x32_bf16 v[90:93], v[156:159], v[224:227], v[90:93]
	v_mfma_f32_16x16x32_bf16 v[86:89], v[164:167], v[224:227], v[86:89]
	v_mfma_f32_16x16x32_bf16 v[82:85], v[168:171], v[190:193], v[82:85]
	v_mfma_f32_16x16x32_bf16 v[94:97], v[182:185], v[190:193], v[94:97]
	v_mfma_f32_16x16x32_bf16 v[110:113], v[168:171], v[198:201], v[110:113]
	v_mfma_f32_16x16x32_bf16 v[118:121], v[182:185], v[198:201], v[118:121]
	v_mfma_f32_16x16x32_bf16 v[114:117], v[168:171], v[206:209], v[114:117]
	v_mfma_f32_16x16x32_bf16 v[98:101], v[182:185], v[206:209], v[98:101]
	v_mfma_f32_16x16x32_bf16 v[70:73], v[168:171], v[214:217], v[70:73]
	v_mfma_f32_16x16x32_bf16 v[66:69], v[182:185], v[214:217], v[66:69]
	v_mfma_f32_16x16x32_bf16 v[82:85], v[172:175], v[194:197], v[82:85]
	v_mfma_f32_16x16x32_bf16 v[94:97], v[186:189], v[194:197], v[94:97]
	v_mfma_f32_16x16x32_bf16 v[110:113], v[172:175], v[202:205], v[110:113]
	v_mfma_f32_16x16x32_bf16 v[118:121], v[186:189], v[202:205], v[118:121]
	v_mfma_f32_16x16x32_bf16 v[114:117], v[172:175], v[210:213], v[114:117]
	v_mfma_f32_16x16x32_bf16 v[98:101], v[186:189], v[210:213], v[98:101]
	v_mfma_f32_16x16x32_bf16 v[70:73], v[172:175], v[224:227], v[70:73]
	v_mfma_f32_16x16x32_bf16 v[66:69], v[186:189], v[224:227], v[66:69]
	s_setprio 0
	s_barrier
; #define PG8_STAGE(bufoff, gbase, voff) do { _Pragma("unroll") for (int _i = 0; _i < 2; ++_i) \
;         __builtin_amdgcn_global_load_lds((const unsigned*)((const char*)(gbase) + (voff)[_i]), (PG8_LAS unsigned*)(lds + (bufoff) + ldsw + _i * 8192), 16, 0, 0); } while (0)
; #define PG8_LDA(dst, b, h) do { _Pragma("unroll") for (int m = 0; m < 4; ++m) _Pragma("unroll") for (int k = 0; k < 2; ++k) dst[m][k] = *(const PG8_LAS bf16x8*)(lds + PG8_SA(b, h) + aoff + m * 2048 + k * 1024); } while (0)
; #define PG8_MMA(ai, bj, At, Bt) do { __builtin_amdgcn_s_setprio(1); _Pragma("unroll") for (int m = 0; m < 4; ++m) _Pragma("unroll") for (int n = 0; n < 2; ++n) _Pragma("unroll") for (int k = 0; k < 2; ++k) \
;         acc[ai][bj][m][n] = __builtin_amdgcn_mfma_f32_16x16x32_bf16(Bt[n][k], At[m][k], acc[ai][bj][m][n], 0, 0, 0); __builtin_amdgcn_s_setprio(0); } while (0)
; #define PG8_WAIT_V(n) asm volatile("s_waitcnt vmcnt(" #n ")" ::: "memory")
; #define PG8_WAIT_L(n) asm volatile("s_waitcnt lgkmcnt(" #n ")" ::: "memory")
; #define PG8_BAR __builtin_amdgcn_s_barrier()
; #define PG8_SCHED __builtin_amdgcn_sched_barrier(0)
; template <class Epi, class Sched, bool ALIGN_EPI = false, bool SP2 = false>
; __device__ __forceinline__ void gemm_phase(PG8_LAS unsigned char* lds, const Gemm g, const Sched& S, const Epi& E) {
;     ...
;         for (int t = 0; t < nt; t += 2) {
;     ...
;             PG8_LDA(At, 1, 1); PG8_STAGE(PG8_SB(1, 0), b3, voffB); PG8_STAGE(PG8_SB(1, 1), b3 + hstep, voffB); PG8_STAGE(PG8_SA(1, 0), a3, voffA);
;             PG8_WAIT_V(8); PG8_WAIT_L(0); PG8_BAR; PG8_MMA(1, 0, At, B0); PG8_MMA(1, 1, At, B1); PG8_BAR; PG8_SCHED;
	s_add_i32 s30, s48, s42
	v_lshl_add_u64 v[176:177], v[176:177], 0, s[64:65]
	s_mov_b32 m0, s30
	ds_read_b128 v[190:193], v181 offset:49152
	ds_read_b128 v[194:197], v181 offset:50176
	ds_read_b128 v[198:201], v181 offset:51200
	ds_read_b128 v[202:205], v181 offset:52224
	ds_read_b128 v[206:209], v181 offset:53248
	ds_read_b128 v[210:213], v181 offset:54272
	ds_read_b128 v[214:217], v181 offset:55296
	ds_read_b128 v[224:227], v181 offset:56320
	global_load_lds_dwordx4 v[176:177], off
	s_add_i32 m0, s30, 0x2000
	s_add_u32 s28, s28, 0x80080
	v_lshl_add_u64 v[176:177], v[218:219], 0, s[64:65]
	s_addc_u32 s29, s29, 0
	s_add_i32 s30, s91, s42
	global_load_lds_dwordx4 v[176:177], off
	v_lshl_add_u64 v[176:177], s[28:29], 0, v[0:1]
	s_mov_b32 m0, s30
	s_nop 0
	global_load_lds_dwordx4 v[176:177], off
	v_lshl_add_u64 v[176:177], s[28:29], 0, v[126:127]
	s_add_i32 m0, s30, 0x2000
	s_nop 0
	global_load_lds_dwordx4 v[176:177], off
	v_lshl_add_u64 v[176:177], v[220:221], 0, s[64:65]
	s_mov_b32 m0, s86
	s_nop 0
	global_load_lds_dwordx4 v[176:177], off
	v_lshl_add_u64 v[176:177], v[222:223], 0, s[64:65]
	s_mov_b32 m0, s87
	s_nop 0
	global_load_lds_dwordx4 v[176:177], off
	s_waitcnt vmcnt(8)
	s_waitcnt lgkmcnt(0)
	s_barrier
	s_setprio 1
	v_mfma_f32_16x16x32_bf16 v[62:65], v[152:155], v[190:193], v[62:65]
	v_mfma_f32_16x16x32_bf16 v[58:61], v[160:163], v[190:193], v[58:61]
	v_mfma_f32_16x16x32_bf16 v[46:49], v[152:155], v[198:201], v[46:49]
	v_mfma_f32_16x16x32_bf16 v[42:45], v[160:163], v[198:201], v[42:45]
	v_mfma_f32_16x16x32_bf16 v[30:33], v[152:155], v[206:209], v[30:33]
	v_mfma_f32_16x16x32_bf16 v[26:29], v[160:163], v[206:209], v[26:29]
	v_mfma_f32_16x16x32_bf16 v[14:17], v[152:155], v[214:217], v[14:17]
	v_mfma_f32_16x16x32_bf16 v[10:13], v[160:163], v[214:217], v[10:13]
	v_mfma_f32_16x16x32_bf16 v[62:65], v[156:159], v[194:197], v[62:65]
	v_mfma_f32_16x16x32_bf16 v[58:61], v[164:167], v[194:197], v[58:61]
	v_mfma_f32_16x16x32_bf16 v[46:49], v[156:159], v[202:205], v[46:49]
	v_mfma_f32_16x16x32_bf16 v[42:45], v[164:167], v[202:205], v[42:45]
	v_mfma_f32_16x16x32_bf16 v[30:33], v[156:159], v[210:213], v[30:33]
	v_mfma_f32_16x16x32_bf16 v[26:29], v[164:167], v[210:213], v[26:29]
	v_mfma_f32_16x16x32_bf16 v[14:17], v[156:159], v[224:227], v[14:17]
	v_mfma_f32_16x16x32_bf16 v[10:13], v[164:167], v[224:227], v[10:13]
	v_mfma_f32_16x16x32_bf16 v[54:57], v[168:171], v[190:193], v[54:57]
	v_mfma_f32_16x16x32_bf16 v[50:53], v[182:185], v[190:193], v[50:53]
	v_mfma_f32_16x16x32_bf16 v[38:41], v[168:171], v[198:201], v[38:41]
	v_mfma_f32_16x16x32_bf16 v[34:37], v[182:185], v[198:201], v[34:37]
	v_mfma_f32_16x16x32_bf16 v[22:25], v[168:171], v[206:209], v[22:25]
	v_mfma_f32_16x16x32_bf16 v[18:21], v[182:185], v[206:209], v[18:21]
	v_mfma_f32_16x16x32_bf16 v[6:9], v[168:171], v[214:217], v[6:9]
	v_mfma_f32_16x16x32_bf16 v[2:5], v[182:185], v[214:217], v[2:5]
	v_mfma_f32_16x16x32_bf16 v[54:57], v[172:175], v[194:197], v[54:57]
	v_mfma_f32_16x16x32_bf16 v[50:53], v[186:189], v[194:197], v[50:53]
	v_mfma_f32_16x16x32_bf16 v[38:41], v[172:175], v[202:205], v[38:41]
	v_mfma_f32_16x16x32_bf16 v[34:37], v[186:189], v[202:205], v[34:37]
	v_mfma_f32_16x16x32_bf16 v[22:25], v[172:175], v[210:213], v[22:25]
	v_mfma_f32_16x16x32_bf16 v[18:21], v[186:189], v[210:213], v[18:21]
	v_mfma_f32_16x16x32_bf16 v[6:9], v[172:175], v[224:227], v[6:9]
	v_mfma_f32_16x16x32_bf16 v[2:5], v[186:189], v[224:227], v[2:5]
	s_setprio 0
	s_barrier
	s_add_i32 s81, s81, 2
	s_add_u32 s0, s0, 0x100
	s_addc_u32 s1, s1, 0
	s_add_u32 s41, s41, 0x100
	s_addc_u32 s67, s67, 0
	s_cmp_gt_u32 s81, 29
	s_cbranch_scc0 .LBB0_910
	s_and_b64 vcc, exec, s[18:19]
	s_cbranch_vccz .LBB0_913
	s_barrier

;     __device__ __forceinline__ bool next(int i, Unit& u) const { if (i > 0 || c < first) return false; const int idx = c - first; u.pm = idx % nM; u.pn = idx / nM; return true; }
; #define PG8_STAGE(bufoff, gbase, voff) do { _Pragma("unroll") for (int _i = 0; _i < 2; ++_i) \
;         __builtin_amdgcn_global_load_lds((const unsigned*)((const char*)(gbase) + (voff)[_i]), (PG8_LAS unsigned*)(lds + (bufoff) + ldsw + _i * 8192), 16, 0, 0); } while (0)
; #define PG8_LDA(dst, b, h) do { _Pragma("unroll") for (int m = 0; m < 4; ++m) _Pragma("unroll") for (int k = 0; k < 2; ++k) dst[m][k] = *(const PG8_LAS bf16x8*)(lds + PG8_SA(b, h) + aoff + m * 2048 + k * 1024); } while (0)
; #define PG8_WAIT_V(n) asm volatile("s_waitcnt vmcnt(" #n ")" ::: "memory")
; #define PG8_WAIT_L(n) asm volatile("s_waitcnt lgkmcnt(" #n ")" ::: "memory")
; #define PG8_BAR __builtin_amdgcn_s_barrier()
; template <class Epi, class Sched, bool ALIGN_EPI = false, bool SP2 = false>
; __device__ __forceinline__ void gemm_phase(PG8_LAS unsigned char* lds, const Gemm g, const Sched& S, const Epi& E) {
;     ...
;         const bool has_next = S.next(ui + 1, nxt);
;         const char* nA = has_next ? (const char*)g.A + (size_t)nxt.pm * tstep : cA; const char* nB = has_next ? (const char*)g.Bt + (size_t)nxt.pn * tstep : cB;
;         for (int t = 0; t < nt; t += 2) {
;             if constexpr (Epi::HAS_MID) { if (t == Epi::MID0 || t == Epi::MID1) E.mid(acc, cur, wr, wc, fr, fq, t == Epi::MID0 ? 0 : 1); }
;             const bool last = (t == nt - 2);
;             const char* a1 = cA + (size_t)(t + 1) * kstep;
;             const char* a2 = last ? nA : cA + (size_t)(t + 2) * kstep; const char* b2 = last ? nB : cB + (size_t)(t + 2) * kstep;
;             const char* a3 = a2 + kstep; const char* b3 = b2 + kstep;
;             if (last && has_next) S.a_ready(nxt);
;             if constexpr (SP2) {
;             PG8_LDB(B0, 0, 0); PG8_LDB(B1, 0, 1); PG8_SCHED; PG8_LDA(At, 0, 0); PG8_STAGE(PG8_SA(1, 1), a1 + hstep, voffA);
;             PG8_WAIT_V(8); PG8_WAIT_L(0); PG8_BAR; PG8_MMA(0, 0, At, B0); PG8_MMA(0, 1, At, B1); PG8_BAR; PG8_SCHED;
;             PG8_LDA(At, 0, 1); PG8_STAGE(PG8_SB(0, 0), b2, voffB); PG8_STAGE(PG8_SB(0, 1), b2 + hstep, voffB); PG8_STAGE(PG8_SA(0, 0), a2, voffA);
;             PG8_WAIT_V(8); PG8_WAIT_L(0); PG8_BAR; PG8_MMA(1, 0, At, B0); PG8_MMA(1, 1, At, B1); PG8_BAR; PG8_SCHED;
.LBB0_963:
	s_add_u32 s24, s0, 0xfff80080
	s_addc_u32 s25, s1, -1
	s_add_i32 s43, 0, 0x10000
	s_cmp_eq_u32 s42, 28
	s_cselect_b32 s27, s13, s25
	s_cselect_b32 s26, s17, s24
	s_cselect_b32 s25, s19, s41
	s_cselect_b32 s24, s29, s40
	s_add_i32 s48, 0, 0x14000
	v_add_u32_e32 v164, s43, v197
	v_add_u32_e32 v180, s48, v197
	ds_read_b128 v[152:155], v164
	ds_read_b128 v[156:159], v164 offset:1024
	ds_read_b128 v[160:163], v164 offset:2048
	ds_read_b128 v[164:167], v164 offset:3072
	ds_read_b128 v[168:171], v180
	ds_read_b128 v[172:175], v180 offset:1024
	ds_read_b128 v[176:179], v180 offset:2048
	ds_read_b128 v[180:183], v180 offset:3072
	v_lshl_add_u64 v[220:221], s[0:1], 0, v[148:149]
	s_add_i32 m0, s31, 0xc000
	ds_read_b128 v[184:187], v199
	ds_read_b128 v[188:191], v199 offset:1024
	ds_read_b128 v[192:195], v199 offset:2048
	ds_read_b128 v[200:203], v199 offset:3072
	ds_read_b128 v[204:207], v199 offset:4096
	ds_read_b128 v[208:211], v199 offset:5120
	ds_read_b128 v[212:215], v199 offset:6144
	ds_read_b128 v[216:219], v199 offset:7168
	global_load_lds_dwordx4 v[220:221], off
	v_lshl_add_u64 v[220:221], s[0:1], 0, v[150:151]
	s_add_i32 m0, s31, 0xe000
	s_nop 0
	global_load_lds_dwordx4 v[220:221], off
	s_waitcnt vmcnt(8)
	s_waitcnt lgkmcnt(0)
	s_barrier
	s_setprio 1
	v_mfma_f32_16x16x32_bf16 v[144:147], v[152:155], v[184:187], v[144:147]
	v_mfma_f32_16x16x32_bf16 v[122:125], v[160:163], v[184:187], v[122:125]
	v_mfma_f32_16x16x32_bf16 v[110:113], v[152:155], v[192:195], v[110:113]
	v_mfma_f32_16x16x32_bf16 v[106:109], v[160:163], v[192:195], v[106:109]
	v_mfma_f32_16x16x32_bf16 v[94:97], v[152:155], v[204:207], v[94:97]
	v_mfma_f32_16x16x32_bf16 v[90:93], v[160:163], v[204:207], v[90:93]
	v_mfma_f32_16x16x32_bf16 v[78:81], v[152:155], v[212:215], v[78:81]
	v_mfma_f32_16x16x32_bf16 v[74:77], v[160:163], v[212:215], v[74:77]
	v_mfma_f32_16x16x32_bf16 v[144:147], v[156:159], v[188:191], v[144:147]
	v_mfma_f32_16x16x32_bf16 v[122:125], v[164:167], v[188:191], v[122:125]
	v_mfma_f32_16x16x32_bf16 v[110:113], v[156:159], v[200:203], v[110:113]
	v_mfma_f32_16x16x32_bf16 v[106:109], v[164:167], v[200:203], v[106:109]
	v_mfma_f32_16x16x32_bf16 v[94:97], v[156:159], v[208:211], v[94:97]
	v_mfma_f32_16x16x32_bf16 v[90:93], v[164:167], v[208:211], v[90:93]
	v_mfma_f32_16x16x32_bf16 v[78:81], v[156:159], v[216:219], v[78:81]
	v_mfma_f32_16x16x32_bf16 v[74:77], v[164:167], v[216:219], v[74:77]
	v_mfma_f32_16x16x32_bf16 v[118:121], v[168:171], v[184:187], v[118:121]
	v_mfma_f32_16x16x32_bf16 v[114:117], v[176:179], v[184:187], v[114:117]
	v_mfma_f32_16x16x32_bf16 v[102:105], v[168:171], v[192:195], v[102:105]
	v_mfma_f32_16x16x32_bf16 v[98:101], v[176:179], v[192:195], v[98:101]
	v_mfma_f32_16x16x32_bf16 v[86:89], v[168:171], v[204:207], v[86:89]
	v_mfma_f32_16x16x32_bf16 v[82:85], v[176:179], v[204:207], v[82:85]
	v_mfma_f32_16x16x32_bf16 v[70:73], v[168:171], v[212:215], v[70:73]
	v_mfma_f32_16x16x32_bf16 v[66:69], v[176:179], v[212:215], v[66:69]
	v_mfma_f32_16x16x32_bf16 v[118:121], v[172:175], v[188:191], v[118:121]
	v_mfma_f32_16x16x32_bf16 v[114:117], v[180:183], v[188:191], v[114:117]
	v_mfma_f32_16x16x32_bf16 v[102:105], v[172:175], v[200:203], v[102:105]
	v_mfma_f32_16x16x32_bf16 v[98:101], v[180:183], v[200:203], v[98:101]
	v_mfma_f32_16x16x32_bf16 v[86:89], v[172:175], v[208:211], v[86:89]
	v_mfma_f32_16x16x32_bf16 v[82:85], v[180:183], v[208:211], v[82:85]
	v_mfma_f32_16x16x32_bf16 v[70:73], v[172:175], v[216:219], v[70:73]
	v_mfma_f32_16x16x32_bf16 v[66:69], v[180:183], v[216:219], v[66:69]
	s_setprio 0
	s_barrier
	s_add_i32 s43, s43, s30
	v_lshl_add_u64 v[220:221], s[24:25], 0, v[0:1]
	s_mov_b32 m0, s43
	ds_read_b128 v[184:187], v199 offset:16384
	ds_read_b128 v[188:191], v199 offset:17408
	ds_read_b128 v[192:195], v199 offset:18432
	ds_read_b128 v[200:203], v199 offset:19456
	ds_read_b128 v[204:207], v199 offset:20480
	ds_read_b128 v[208:211], v199 offset:21504
	ds_read_b128 v[212:215], v199 offset:22528
	ds_read_b128 v[216:219], v199 offset:23552
	global_load_lds_dwordx4 v[220:221], off
	s_add_i32 m0, s43, 0x2000
	s_add_u32 vcc_lo, s24, 0x80000
	v_lshl_add_u64 v[222:223], s[24:25], 0, v[126:127]
	s_addc_u32 vcc_hi, s25, 0
	s_add_i32 s43, s48, s30
	global_load_lds_dwordx4 v[222:223], off
	v_lshl_add_u64 v[224:225], vcc, 0, v[0:1]
	s_mov_b32 m0, s43
	v_lshl_add_u64 v[226:227], s[26:27], 0, v[126:127]
	global_load_lds_dwordx4 v[224:225], off
	v_lshl_add_u64 v[224:225], vcc, 0, v[126:127]
	s_add_i32 m0, s43, 0x2000
	s_nop 0
	global_load_lds_dwordx4 v[224:225], off
	v_lshl_add_u64 v[224:225], s[26:27], 0, v[0:1]
	s_mov_b32 m0, s31
	s_nop 0
	global_load_lds_dwordx4 v[224:225], off
	s_mov_b32 m0, s34
	s_nop 0
	global_load_lds_dwordx4 v[226:227], off
	s_waitcnt vmcnt(8)
	s_waitcnt lgkmcnt(0)
	s_barrier
; #define PG8_STAGE(bufoff, gbase, voff) do { _Pragma("unroll") for (int _i = 0; _i < 2; ++_i) \
;         __builtin_amdgcn_global_load_lds((const unsigned*)((const char*)(gbase) + (voff)[_i]), (PG8_LAS unsigned*)(lds + (bufoff) + ldsw + _i * 8192), 16, 0, 0); } while (0)
; #define PG8_LDA(dst, b, h) do { _Pragma("unroll") for (int m = 0; m < 4; ++m) _Pragma("unroll") for (int k = 0; k < 2; ++k) dst[m][k] = *(const PG8_LAS bf16x8*)(lds + PG8_SA(b, h) + aoff + m * 2048 + k * 1024); } while (0)
; #define PG8_LDB(dst, b, h) do { _Pragma("unroll") for (int n = 0; n < 2; ++n) _Pragma("unroll") for (int k = 0; k < 2; ++k) dst[n][k] = *(const PG8_LAS bf16x8*)(lds + PG8_SB(b, h) + boff + n * 2048 + k * 1024); } while (0)
; #define PG8_MMA(ai, bj, At, Bt) do { __builtin_amdgcn_s_setprio(1); _Pragma("unroll") for (int m = 0; m < 4; ++m) _Pragma("unroll") for (int n = 0; n < 2; ++n) _Pragma("unroll") for (int k = 0; k < 2; ++k) \
;         acc[ai][bj][m][n] = __builtin_amdgcn_mfma_f32_16x16x32_bf16(Bt[n][k], At[m][k], acc[ai][bj][m][n], 0, 0, 0); __builtin_amdgcn_s_setprio(0); } while (0)
; #define PG8_WAIT_V(n) asm volatile("s_waitcnt vmcnt(" #n ")" ::: "memory")
; #define PG8_WAIT_L(n) asm volatile("s_waitcnt lgkmcnt(" #n ")" ::: "memory")
; #define PG8_BAR __builtin_amdgcn_s_barrier()
; #define PG8_SCHED __builtin_amdgcn_sched_barrier(0)
; template <class Epi, class Sched, bool ALIGN_EPI = false, bool SP2 = false>
; __device__ __forceinline__ void gemm_phase(PG8_LAS unsigned char* lds, const Gemm g, const Sched& S, const Epi& E) {
;     ...
;             PG8_WAIT_V(8); PG8_WAIT_L(0); PG8_BAR; PG8_MMA(1, 0, At, B0); PG8_MMA(1, 1, At, B1); PG8_BAR; PG8_SCHED;
;             PG8_LDB(B0, 1, 0); PG8_LDB(B1, 1, 1); PG8_SCHED; PG8_LDA(At, 1, 0); PG8_STAGE(PG8_SA(0, 1), a2 + hstep, voffA);
;             PG8_WAIT_V(8); PG8_WAIT_L(0); PG8_BAR; PG8_MMA(0, 0, At, B0); PG8_MMA(0, 1, At, B1); PG8_BAR; PG8_SCHED;
	s_setprio 1
	v_mfma_f32_16x16x32_bf16 v[62:65], v[152:155], v[184:187], v[62:65]
	v_mfma_f32_16x16x32_bf16 v[58:61], v[160:163], v[184:187], v[58:61]
	v_mfma_f32_16x16x32_bf16 v[46:49], v[152:155], v[192:195], v[46:49]
	v_mfma_f32_16x16x32_bf16 v[42:45], v[160:163], v[192:195], v[42:45]
	v_mfma_f32_16x16x32_bf16 v[30:33], v[152:155], v[204:207], v[30:33]
	v_mfma_f32_16x16x32_bf16 v[26:29], v[160:163], v[204:207], v[26:29]
	v_mfma_f32_16x16x32_bf16 v[14:17], v[152:155], v[212:215], v[14:17]
	v_mfma_f32_16x16x32_bf16 v[10:13], v[160:163], v[212:215], v[10:13]
	v_mfma_f32_16x16x32_bf16 v[62:65], v[156:159], v[188:191], v[62:65]
	v_mfma_f32_16x16x32_bf16 v[58:61], v[164:167], v[188:191], v[58:61]
	v_mfma_f32_16x16x32_bf16 v[46:49], v[156:159], v[200:203], v[46:49]
	v_mfma_f32_16x16x32_bf16 v[42:45], v[164:167], v[200:203], v[42:45]
	v_mfma_f32_16x16x32_bf16 v[30:33], v[156:159], v[208:211], v[30:33]
	v_mfma_f32_16x16x32_bf16 v[26:29], v[164:167], v[208:211], v[26:29]
	v_mfma_f32_16x16x32_bf16 v[14:17], v[156:159], v[216:219], v[14:17]
	v_mfma_f32_16x16x32_bf16 v[10:13], v[164:167], v[216:219], v[10:13]
	v_mfma_f32_16x16x32_bf16 v[54:57], v[168:171], v[184:187], v[54:57]
	v_mfma_f32_16x16x32_bf16 v[50:53], v[176:179], v[184:187], v[50:53]
	v_mfma_f32_16x16x32_bf16 v[38:41], v[168:171], v[192:195], v[38:41]
	v_mfma_f32_16x16x32_bf16 v[34:37], v[176:179], v[192:195], v[34:37]
	v_mfma_f32_16x16x32_bf16 v[22:25], v[168:171], v[204:207], v[22:25]
	v_mfma_f32_16x16x32_bf16 v[18:21], v[176:179], v[204:207], v[18:21]
	v_mfma_f32_16x16x32_bf16 v[6:9], v[168:171], v[212:215], v[6:9]
	v_mfma_f32_16x16x32_bf16 v[2:5], v[176:179], v[212:215], v[2:5]
	v_mfma_f32_16x16x32_bf16 v[54:57], v[172:175], v[188:191], v[54:57]
	v_mfma_f32_16x16x32_bf16 v[50:53], v[180:183], v[188:191], v[50:53]
	v_mfma_f32_16x16x32_bf16 v[38:41], v[172:175], v[200:203], v[38:41]
	v_mfma_f32_16x16x32_bf16 v[34:37], v[180:183], v[200:203], v[34:37]
	v_mfma_f32_16x16x32_bf16 v[22:25], v[172:175], v[208:211], v[22:25]
	v_mfma_f32_16x16x32_bf16 v[18:21], v[180:183], v[208:211], v[18:21]
	v_mfma_f32_16x16x32_bf16 v[6:9], v[172:175], v[216:219], v[6:9]
	v_mfma_f32_16x16x32_bf16 v[2:5], v[180:183], v[216:219], v[2:5]
	s_setprio 0
	s_barrier
	s_add_i32 s43, 0, 0x18000
	s_add_i32 s48, 0, 0x1c000
	v_add_u32_e32 v164, s43, v197
	v_add_u32_e32 v180, s48, v197
	ds_read_b128 v[152:155], v164
	ds_read_b128 v[156:159], v164 offset:1024
	ds_read_b128 v[160:163], v164 offset:2048
	ds_read_b128 v[164:167], v164 offset:3072
	ds_read_b128 v[168:171], v180
	ds_read_b128 v[172:175], v180 offset:1024
	ds_read_b128 v[176:179], v180 offset:2048
	ds_read_b128 v[180:183], v180 offset:3072
	s_add_u32 s26, s26, 0x80000
	s_addc_u32 s27, s27, 0
	s_mov_b32 m0, s35
	v_lshl_add_u64 v[228:229], s[26:27], 0, v[0:1]
	ds_read_b128 v[184:187], v199 offset:32768
	ds_read_b128 v[188:191], v199 offset:33792
	ds_read_b128 v[192:195], v199 offset:34816
	ds_read_b128 v[200:203], v199 offset:35840
	ds_read_b128 v[204:207], v199 offset:36864
	ds_read_b128 v[208:211], v199 offset:37888
	ds_read_b128 v[212:215], v199 offset:38912
	ds_read_b128 v[216:219], v199 offset:39936
	global_load_lds_dwordx4 v[228:229], off
	v_lshl_add_u64 v[228:229], s[26:27], 0, v[126:127]
	s_mov_b32 m0, s76
	s_nop 0
	global_load_lds_dwordx4 v[228:229], off
	s_waitcnt vmcnt(8)
	s_waitcnt lgkmcnt(0)
	s_barrier
	s_setprio 1
	v_mfma_f32_16x16x32_bf16 v[144:147], v[152:155], v[184:187], v[144:147]
	v_mfma_f32_16x16x32_bf16 v[122:125], v[160:163], v[184:187], v[122:125]
	v_mfma_f32_16x16x32_bf16 v[110:113], v[152:155], v[192:195], v[110:113]
	v_mfma_f32_16x16x32_bf16 v[106:109], v[160:163], v[192:195], v[106:109]
	v_mfma_f32_16x16x32_bf16 v[94:97], v[152:155], v[204:207], v[94:97]
	v_mfma_f32_16x16x32_bf16 v[90:93], v[160:163], v[204:207], v[90:93]
	v_mfma_f32_16x16x32_bf16 v[78:81], v[152:155], v[212:215], v[78:81]
	v_mfma_f32_16x16x32_bf16 v[74:77], v[160:163], v[212:215], v[74:77]
	v_mfma_f32_16x16x32_bf16 v[144:147], v[156:159], v[188:191], v[144:147]
	v_mfma_f32_16x16x32_bf16 v[122:125], v[164:167], v[188:191], v[122:125]
	v_mfma_f32_16x16x32_bf16 v[110:113], v[156:159], v[200:203], v[110:113]
	v_mfma_f32_16x16x32_bf16 v[106:109], v[164:167], v[200:203], v[106:109]
	v_mfma_f32_16x16x32_bf16 v[94:97], v[156:159], v[208:211], v[94:97]
	v_mfma_f32_16x16x32_bf16 v[90:93], v[164:167], v[208:211], v[90:93]
	v_mfma_f32_16x16x32_bf16 v[78:81], v[156:159], v[216:219], v[78:81]
	v_mfma_f32_16x16x32_bf16 v[74:77], v[164:167], v[216:219], v[74:77]
	v_mfma_f32_16x16x32_bf16 v[118:121], v[168:171], v[184:187], v[118:121]
	v_mfma_f32_16x16x32_bf16 v[114:117], v[176:179], v[184:187], v[114:117]
	v_mfma_f32_16x16x32_bf16 v[102:105], v[168:171], v[192:195], v[102:105]
	v_mfma_f32_16x16x32_bf16 v[98:101], v[176:179], v[192:195], v[98:101]
	v_mfma_f32_16x16x32_bf16 v[86:89], v[168:171], v[204:207], v[86:89]
	v_mfma_f32_16x16x32_bf16 v[82:85], v[176:179], v[204:207], v[82:85]
	v_mfma_f32_16x16x32_bf16 v[70:73], v[168:171], v[212:215], v[70:73]
	v_mfma_f32_16x16x32_bf16 v[66:69], v[176:179], v[212:215], v[66:69]
	v_mfma_f32_16x16x32_bf16 v[118:121], v[172:175], v[188:191], v[118:121]
	v_mfma_f32_16x16x32_bf16 v[114:117], v[180:183], v[188:191], v[114:117]
	v_mfma_f32_16x16x32_bf16 v[102:105], v[172:175], v[200:203], v[102:105]
	v_mfma_f32_16x16x32_bf16 v[98:101], v[180:183], v[200:203], v[98:101]
	v_mfma_f32_16x16x32_bf16 v[86:89], v[172:175], v[208:211], v[86:89]
	v_mfma_f32_16x16x32_bf16 v[82:85], v[180:183], v[208:211], v[82:85]
	v_mfma_f32_16x16x32_bf16 v[70:73], v[172:175], v[216:219], v[70:73]
	v_mfma_f32_16x16x32_bf16 v[66:69], v[180:183], v[216:219], v[66:69]
	s_setprio 0
	s_barrier
; #define PG8_STAGE(bufoff, gbase, voff) do { _Pragma("unroll") for (int _i = 0; _i < 2; ++_i) \
;         __builtin_amdgcn_global_load_lds((const unsigned*)((const char*)(gbase) + (voff)[_i]), (PG8_LAS unsigned*)(lds + (bufoff) + ldsw + _i * 8192), 16, 0, 0); } while (0)
; #define PG8_LDA(dst, b, h) do { _Pragma("unroll") for (int m = 0; m < 4; ++m) _Pragma("unroll") for (int k = 0; k < 2; ++k) dst[m][k] = *(const PG8_LAS bf16x8*)(lds + PG8_SA(b, h) + aoff + m * 2048 + k * 1024); } while (0)
; #define PG8_MMA(ai, bj, At, Bt) do { __builtin_amdgcn_s_setprio(1); _Pragma("unroll") for (int m = 0; m < 4; ++m) _Pragma("unroll") for (int n = 0; n < 2; ++n) _Pragma("unroll") for (int k = 0; k < 2; ++k) \
;         acc[ai][bj][m][n] = __builtin_amdgcn_mfma_f32_16x16x32_bf16(Bt[n][k], At[m][k], acc[ai][bj][m][n], 0, 0, 0); __builtin_amdgcn_s_setprio(0); } while (0)
; #define PG8_WAIT_V(n) asm volatile("s_waitcnt vmcnt(" #n ")" ::: "memory")
; #define PG8_WAIT_L(n) asm volatile("s_waitcnt lgkmcnt(" #n ")" ::: "memory")
; #define PG8_BAR __builtin_amdgcn_s_barrier()
; #define PG8_SCHED __builtin_amdgcn_sched_barrier(0)
; template <class Epi, class Sched, bool ALIGN_EPI = false, bool SP2 = false>
; __device__ __forceinline__ void gemm_phase(PG8_LAS unsigned char* lds, const Gemm g, const Sched& S, const Epi& E) {
;     ...
;         for (int t = 0; t < nt; t += 2) {
;     ...
;             PG8_LDA(At, 1, 1); PG8_STAGE(PG8_SB(1, 0), b3, voffB); PG8_STAGE(PG8_SB(1, 1), b3 + hstep, voffB); PG8_STAGE(PG8_SA(1, 0), a3, voffA);
;             PG8_WAIT_V(8); PG8_WAIT_L(0); PG8_BAR; PG8_MMA(1, 0, At, B0); PG8_MMA(1, 1, At, B1); PG8_BAR; PG8_SCHED;
	s_add_i32 s26, s43, s30
	v_lshl_add_u64 v[220:221], v[220:221], 0, s[64:65]
	s_mov_b32 m0, s26
	ds_read_b128 v[184:187], v199 offset:49152
	ds_read_b128 v[188:191], v199 offset:50176
	ds_read_b128 v[192:195], v199 offset:51200
	ds_read_b128 v[200:203], v199 offset:52224
	ds_read_b128 v[204:207], v199 offset:53248
	ds_read_b128 v[208:211], v199 offset:54272
	ds_read_b128 v[212:215], v199 offset:55296
	ds_read_b128 v[216:219], v199 offset:56320
	global_load_lds_dwordx4 v[220:221], off
	s_add_i32 m0, s26, 0x2000
	s_add_u32 s24, s24, 0x80080
	v_lshl_add_u64 v[220:221], v[222:223], 0, s[64:65]
	s_addc_u32 s25, s25, 0
	s_add_i32 s26, s48, s30
	global_load_lds_dwordx4 v[220:221], off
	v_lshl_add_u64 v[220:221], s[24:25], 0, v[0:1]
	s_mov_b32 m0, s26
	s_nop 0
	global_load_lds_dwordx4 v[220:221], off
	v_lshl_add_u64 v[220:221], s[24:25], 0, v[126:127]
	s_add_i32 m0, s26, 0x2000
	s_nop 0
	global_load_lds_dwordx4 v[220:221], off
	v_lshl_add_u64 v[220:221], v[224:225], 0, s[64:65]
	s_mov_b32 m0, s82
	s_nop 0
	global_load_lds_dwordx4 v[220:221], off
	v_lshl_add_u64 v[220:221], v[226:227], 0, s[64:65]
	s_mov_b32 m0, s83
	s_nop 0
	global_load_lds_dwordx4 v[220:221], off
	s_waitcnt vmcnt(8)
	s_waitcnt lgkmcnt(0)
	s_barrier
	s_setprio 1
	v_mfma_f32_16x16x32_bf16 v[62:65], v[152:155], v[184:187], v[62:65]
	v_mfma_f32_16x16x32_bf16 v[58:61], v[160:163], v[184:187], v[58:61]
	v_mfma_f32_16x16x32_bf16 v[46:49], v[152:155], v[192:195], v[46:49]
	v_mfma_f32_16x16x32_bf16 v[42:45], v[160:163], v[192:195], v[42:45]
	v_mfma_f32_16x16x32_bf16 v[30:33], v[152:155], v[204:207], v[30:33]
	v_mfma_f32_16x16x32_bf16 v[26:29], v[160:163], v[204:207], v[26:29]
	v_mfma_f32_16x16x32_bf16 v[14:17], v[152:155], v[212:215], v[14:17]
	v_mfma_f32_16x16x32_bf16 v[10:13], v[160:163], v[212:215], v[10:13]
	v_mfma_f32_16x16x32_bf16 v[62:65], v[156:159], v[188:191], v[62:65]
	v_mfma_f32_16x16x32_bf16 v[58:61], v[164:167], v[188:191], v[58:61]
	v_mfma_f32_16x16x32_bf16 v[46:49], v[156:159], v[200:203], v[46:49]
	v_mfma_f32_16x16x32_bf16 v[42:45], v[164:167], v[200:203], v[42:45]
	v_mfma_f32_16x16x32_bf16 v[30:33], v[156:159], v[208:211], v[30:33]
	v_mfma_f32_16x16x32_bf16 v[26:29], v[164:167], v[208:211], v[26:29]
	v_mfma_f32_16x16x32_bf16 v[14:17], v[156:159], v[216:219], v[14:17]
	v_mfma_f32_16x16x32_bf16 v[10:13], v[164:167], v[216:219], v[10:13]
	v_mfma_f32_16x16x32_bf16 v[54:57], v[168:171], v[184:187], v[54:57]
	v_mfma_f32_16x16x32_bf16 v[50:53], v[176:179], v[184:187], v[50:53]
	v_mfma_f32_16x16x32_bf16 v[38:41], v[168:171], v[192:195], v[38:41]
	v_mfma_f32_16x16x32_bf16 v[34:37], v[176:179], v[192:195], v[34:37]
	v_mfma_f32_16x16x32_bf16 v[22:25], v[168:171], v[204:207], v[22:25]
	v_mfma_f32_16x16x32_bf16 v[18:21], v[176:179], v[204:207], v[18:21]
	v_mfma_f32_16x16x32_bf16 v[6:9], v[168:171], v[212:215], v[6:9]
	v_mfma_f32_16x16x32_bf16 v[2:5], v[176:179], v[212:215], v[2:5]
	v_mfma_f32_16x16x32_bf16 v[54:57], v[172:175], v[188:191], v[54:57]
	v_mfma_f32_16x16x32_bf16 v[50:53], v[180:183], v[188:191], v[50:53]
	v_mfma_f32_16x16x32_bf16 v[38:41], v[172:175], v[200:203], v[38:41]
	v_mfma_f32_16x16x32_bf16 v[34:37], v[180:183], v[200:203], v[34:37]
	v_mfma_f32_16x16x32_bf16 v[22:25], v[172:175], v[208:211], v[22:25]
	v_mfma_f32_16x16x32_bf16 v[18:21], v[180:183], v[208:211], v[18:21]
	v_mfma_f32_16x16x32_bf16 v[6:9], v[172:175], v[216:219], v[6:9]
	v_mfma_f32_16x16x32_bf16 v[2:5], v[180:183], v[216:219], v[2:5]
	s_setprio 0
	s_barrier
	s_add_i32 s42, s42, 2
	s_add_u32 s0, s0, 0x100
	s_addc_u32 s1, s1, 0
	s_add_u32 s40, s40, 0x100
	s_addc_u32 s41, s41, 0
	s_cmp_gt_u32 s42, 29
	s_cbranch_scc0 .LBB0_963
	s_and_b64 vcc, exec, s[14:15]
	s_cbranch_vccz .LBB0_966
	s_barrier
